# shared-LDS attention with a static slot schedule: fragment read bases per slot precomputed in VGPRs, DMA targets immediate, pre-context steps unrolled, incremental scalars (about 10 instead of 60 scal
# speedup vs baseline: 1.0056x; 1.0056x over previous
.LBB0_465:
	v_add_f32_e32 v1, v1, v4
	v_mul_f32_e32 v4, 0x4f800000, v1
	v_cmp_gt_f32_e32 vcc, s70, v1
	v_add_f32_e32 v2, v2, v3
	v_mul_f32_e32 v3, 0x4f800000, v2
	v_cndmask_b32_e32 v1, v1, v4, vcc
	v_sqrt_f32_e32 v4, v1
	s_mul_i32 s82, s82, 0x88000
	s_lshl_b32 s81, s7, 1
	s_mov_b32 s42, s26
	v_add_u32_e32 v9, -1, v4
	v_fma_f32 v10, -v9, v4, v1
	v_cmp_ge_f32_e64 s[0:1], 0, v10
	v_add_u32_e32 v10, 1, v4
	s_mov_b32 s43, s27
	v_cndmask_b32_e64 v9, v4, v9, s[0:1]
	v_fma_f32 v4, -v10, v4, v1
	v_cmp_lt_f32_e64 s[0:1], 0, v4
	s_or_b32 s20, s5, 1
	s_and_b32 s4, s4, 15
	v_cndmask_b32_e64 v4, v9, v10, s[0:1]
	v_mul_f32_e32 v9, 0x37800000, v4
	v_cndmask_b32_e32 v4, v4, v9, vcc
	v_cmp_gt_f32_e32 vcc, s70, v2
	v_cmp_class_f32_e64 s[0:1], v1, v237
	s_lshl_b32 s4, s4, 10
	v_cndmask_b32_e32 v2, v2, v3, vcc
	v_sqrt_f32_e32 v3, v2
	v_cndmask_b32_e64 v1, v4, v1, s[0:1]
	s_waitcnt lgkmcnt(8)
	v_fma_f32 v1, v227, v1, v228
	v_mov_b32_e32 v224, 0
	v_add_u32_e32 v4, -1, v3
	v_fma_f32 v9, -v4, v3, v2
	v_cmp_ge_f32_e64 s[0:1], 0, v9
	v_add_u32_e32 v9, 1, v3
	s_mov_b32 s92, 0
	v_cndmask_b32_e64 v4, v3, v4, s[0:1]
	v_fma_f32 v3, -v9, v3, v2
	v_cmp_lt_f32_e64 s[0:1], 0, v3
	s_add_i32 s83, s83, 20
	s_add_i32 s84, s75, 4
	v_cndmask_b32_e64 v3, v4, v9, s[0:1]
	v_mul_f32_e32 v4, 0x37800000, v3
	v_cndmask_b32_e32 v3, v3, v4, vcc
	v_add_f32_e32 v4, v5, v6
	v_mul_f32_e32 v5, 0x4f800000, v4
	v_cmp_gt_f32_e32 vcc, s70, v4
	v_cmp_class_f32_e64 s[0:1], v2, v237
	v_mov_b32_e32 v225, v224
	v_cndmask_b32_e32 v4, v4, v5, vcc
	v_sqrt_f32_e32 v5, v4
	v_cndmask_b32_e64 v2, v3, v2, s[0:1]
	v_fma_f32 v2, v227, v2, v228
	v_max3_f32 v1, v1, 0, v2
	v_add_u32_e32 v2, -1, v5
	v_fma_f32 v3, -v2, v5, v4
	v_cmp_ge_f32_e64 s[0:1], 0, v3
	v_add_u32_e32 v3, 1, v5
	v_mov_b32_e32 v222, v224
	v_cndmask_b32_e64 v2, v5, v2, s[0:1]
	v_fma_f32 v5, -v3, v5, v4
	v_cmp_lt_f32_e64 s[0:1], 0, v5
	v_mov_b32_e32 v223, v224
	s_nop 0
	v_cndmask_b32_e64 v2, v2, v3, s[0:1]
	v_mul_f32_e32 v3, 0x37800000, v2
	s_lshl_b32 s0, s8, 1
	v_cndmask_b32_e32 v2, v2, v3, vcc
	v_cmp_class_f32_e32 vcc, v4, v237
	v_add_f32_e32 v3, v7, v8
	s_add_i32 s0, s0, s82
	v_cndmask_b32_e32 v2, v2, v4, vcc
	v_mul_f32_e32 v4, 0x4f800000, v3
	v_cmp_gt_f32_e32 vcc, s70, v3
	s_add_i32 s7, s0, 0x44000
	s_add_i32 s1, s0, 0x4c800
	v_cndmask_b32_e32 v3, v3, v4, vcc
	s_add_i32 s9, s0, 0x8800
	v_sqrt_f32_e32 v52, v3
	v_fma_f32 v2, v227, v2, v228
	v_add_u32_e32 v53, -1, v52
	v_fma_f32 v54, -v53, v52, v3
	v_cmp_ge_f32_e64 s[0:1], 0, v54
	v_add_u32_e32 v54, 1, v52
	s_nop 0
	v_cndmask_b32_e64 v53, v52, v53, s[0:1]
	v_fma_f32 v52, -v54, v52, v3
	v_cmp_lt_f32_e64 s[0:1], 0, v52
	s_nop 1
	v_cndmask_b32_e64 v52, v53, v54, s[0:1]
	v_mul_f32_e32 v53, 0x37800000, v52
	v_cndmask_b32_e32 v52, v52, v53, vcc
	v_cmp_class_f32_e32 vcc, v3, v237
	s_nop 1
	v_cndmask_b32_e32 v3, v52, v3, vcc
	v_fma_f32 v3, v227, v3, v228
	v_max3_f32 v239, v1, v2, v3
	v_add_u32_e32 v1, s59, v232
	v_sub_u32_e32 v1, v229, v1
	v_add_u32_e32 v2, 15, v1
	v_cmp_gt_u32_e64 s[0:1], 16, v2
	v_add_u32_e32 v2, 14, v1
	v_cmp_gt_u32_e64 s[6:7], 16, v2
	v_add_u32_e32 v2, 13, v1
	v_cmp_gt_u32_e64 s[8:9], 16, v2
	v_add_u32_e32 v2, 12, v1
	v_cmp_gt_u32_e64 s[10:11], 16, v2
	v_add_u32_e32 v2, 11, v1
	v_cmp_gt_u32_e64 s[12:13], 16, v2
	v_add_u32_e32 v2, 10, v1
	v_cmp_gt_u32_e64 s[14:15], 16, v2
	v_add_u32_e32 v2, 9, v1
	v_add_u32_e32 v1, 8, v1
	v_cmp_gt_u32_e64 s[18:19], 16, v1
	v_sub_u32_e64 v1, s20, 4 clamp
	v_cmp_gt_u32_e64 s[16:17], 16, v2
	v_readfirstlane_b32 s20, v1
	s_min_u32 s85, s20, 56
	s_or_b32 s20, s5, 2
	v_sub_u32_e64 v1, s20, 4 clamp
	s_or_b32 s5, s5, 3
	v_readfirstlane_b32 s20, v1
	v_sub_u32_e64 v1, s5, 4 clamp
	s_min_u32 s87, s20, 56
	v_readfirstlane_b32 s5, v1
	s_min_u32 s89, s5, 56
	s_lshl_b32 s5, s75, 8
	s_lshl_b32 s20, s59, 2
	s_or_b32 s5, s5, s20
	v_lshrrev_b32_e32 v85, 4, v226
	v_and_b32_e32 v86, 15, v226
	v_lshlrev_b32_e32 v233, 9, v85
	v_lshl_add_u32 v233, v86, 4, v233
	v_lshlrev_b32_e32 v234, 4, v226
	s_lshl_b32 s97, s59, 3
	s_lshl_b32 s90, s59, 5
	s_mov_b32 s83, 0
	s_mov_b32 s77, 0x2000
	s_cmp_eq_u32 s64, 0
	s_cselect_b32 s83, 0x1000, s83
	s_cselect_b32 s77, 0x3000, s77
	s_cmp_eq_u32 s64, 1
	s_cselect_b32 s83, 0x1e00, s83
	s_cselect_b32 s77, 0x3e00, s77
	s_cmp_eq_u32 s64, 2
	s_cselect_b32 s83, 0x2d00, s83
	s_cselect_b32 s77, 0x4d00, s77
	s_cmp_eq_u32 s64, 3
	s_cselect_b32 s83, 0x0, s83
	s_cselect_b32 s77, 0x3c00, s77
	s_cmp_eq_u32 s64, 4
	s_cselect_b32 s83, 0x0, s83
	s_cselect_b32 s77, 0x4b00, s77
	s_add_u32 s20, s97, 0x18000
	s_add_u32 s21, s90, 0x1a000
	v_add_u32_e32 v1, s20, v233
	v_add_u32_e32 v221, s21, v234
	s_add_u32 s20, s97, 0x1c000
	s_add_u32 s21, s90, 0x1e000
	v_add_u32_e32 v2, s20, v233
	v_add_u32_e32 v235, s21, v234
	s_add_u32 s20, s97, 0x20010
	s_add_u32 s21, s90, 0x22010
	v_add_u32_e32 v3, s20, v233
	v_add_u32_e32 v250, s21, v234
	s_add_u32 s20, s97, s83
	s_add_u32 s21, s90, s77
	v_add_u32_e32 v220, s20, v233
	v_add_u32_e32 v254, s21, v234
	s_sub_i32 s63, s88, 3
	s_add_u32 s20, s93, 3
	s_lshl_b32 s21, s20, 16
	s_add_u32 s95, s21, s61
	s_lshl_b32 s21, s20, 7
	s_add_u32 s92, s21, s62
	s_sub_i32 s4, s5, s4
	v_add_u32_e32 v240, s4, v236
	ds_read2_b32 v[204:205], v240 offset0:192 offset1:193
	ds_read2_b32 v[206:207], v240 offset0:194 offset1:195
	ds_read2_b32 v[208:209], v240 offset0:196 offset1:197
	ds_read2_b32 v[210:211], v240 offset0:198 offset1:199
	ds_read2_b32 v[80:81], v240 offset0:128 offset1:129
	ds_read2_b32 v[82:83], v240 offset0:130 offset1:131
	ds_read2_b32 v[84:85], v240 offset0:132 offset1:133
	ds_read2_b32 v[86:87], v240 offset0:134 offset1:135
	ds_read2_b32 v[180:181], v240 offset0:64 offset1:65
	ds_read2_b32 v[182:183], v240 offset0:66 offset1:67
	ds_read2_b32 v[184:185], v240 offset0:68 offset1:69
	ds_read2_b32 v[186:187], v240 offset0:70 offset1:71
	ds_read2_b32 v[212:213], v240 offset0:0 offset1:1
	ds_read2_b32 v[214:215], v240 offset0:2 offset1:3
	ds_read2_b32 v[242:243], v240 offset0:4 offset1:5
	ds_read2_b32 v[244:245], v240 offset0:6 offset1:7
	v_xor_b32_e32 v76, 0x80000000, v239
	v_xor_b32_e32 v77, 0x80000000, v239
	v_xor_b32_e32 v78, 0x80000000, v239
	v_xor_b32_e32 v79, 0x80000000, v239
	v_mov_b32_e32 v96, 0
	v_mov_b32_e32 v97, 0
	v_mov_b32_e32 v98, 0
	v_mov_b32_e32 v99, 0
	v_mov_b32_e32 v88, 0
	v_mov_b32_e32 v89, 0
	v_mov_b32_e32 v90, 0
	v_mov_b32_e32 v91, 0
	v_mov_b32_e32 v72, 0
	v_mov_b32_e32 v73, 0
	v_mov_b32_e32 v74, 0
	v_mov_b32_e32 v75, 0
	v_mov_b32_e32 v68, 0
	v_mov_b32_e32 v69, 0
	v_mov_b32_e32 v70, 0
	v_mov_b32_e32 v71, 0
	v_mov_b32_e32 v222, 0
	v_mov_b32_e32 v64, 0
	v_mov_b32_e32 v65, 0
	v_mov_b32_e32 v66, 0
	v_mov_b32_e32 v67, 0
	v_mov_b32_e32 v60, 0
	v_mov_b32_e32 v61, 0
	v_mov_b32_e32 v62, 0
	v_mov_b32_e32 v63, 0
	v_mov_b32_e32 v56, 0
	v_mov_b32_e32 v57, 0
	v_mov_b32_e32 v58, 0
	v_mov_b32_e32 v59, 0
	v_mov_b32_e32 v52, 0
	v_mov_b32_e32 v53, 0
	v_mov_b32_e32 v54, 0
	v_mov_b32_e32 v55, 0
	v_mov_b32_e32 v223, 0
	v_mov_b32_e32 v128, 0
	v_mov_b32_e32 v129, 0
	v_mov_b32_e32 v130, 0
	v_mov_b32_e32 v131, 0
	v_mov_b32_e32 v124, 0
	v_mov_b32_e32 v125, 0
	v_mov_b32_e32 v126, 0
	v_mov_b32_e32 v127, 0
	v_mov_b32_e32 v120, 0
	v_mov_b32_e32 v121, 0
	v_mov_b32_e32 v122, 0
	v_mov_b32_e32 v123, 0
	v_mov_b32_e32 v116, 0
	v_mov_b32_e32 v117, 0
	v_mov_b32_e32 v118, 0
	v_mov_b32_e32 v119, 0
	v_mov_b32_e32 v224, 0
	v_mov_b32_e32 v112, 0
	v_mov_b32_e32 v113, 0
	v_mov_b32_e32 v114, 0
	v_mov_b32_e32 v115, 0
	v_mov_b32_e32 v108, 0
	v_mov_b32_e32 v109, 0
	v_mov_b32_e32 v110, 0
	v_mov_b32_e32 v111, 0
	v_mov_b32_e32 v104, 0
	v_mov_b32_e32 v105, 0
	v_mov_b32_e32 v106, 0
	v_mov_b32_e32 v107, 0
	v_mov_b32_e32 v100, 0
	v_mov_b32_e32 v101, 0
	v_mov_b32_e32 v102, 0
	v_mov_b32_e32 v103, 0
	v_mov_b32_e32 v225, 0
	s_waitcnt lgkmcnt(0)
	v_sub_f32_e32 v204, v204, v239
	v_sub_f32_e32 v205, v205, v239
	v_sub_f32_e32 v206, v206, v239
	v_sub_f32_e32 v207, v207, v239
	v_sub_f32_e32 v208, v208, v239
	v_sub_f32_e32 v209, v209, v239
	v_sub_f32_e32 v210, v210, v239
	v_sub_f32_e32 v211, v211, v239
	v_cndmask_b32_e64 v204, v238, v204, s[0:1]
	v_cndmask_b32_e64 v205, v238, v205, s[6:7]
	v_cndmask_b32_e64 v206, v238, v206, s[8:9]
	v_cndmask_b32_e64 v207, v238, v207, s[10:11]
	v_cndmask_b32_e64 v208, v238, v208, s[12:13]
	v_cndmask_b32_e64 v209, v238, v209, s[14:15]
	v_cndmask_b32_e64 v210, v238, v210, s[16:17]
	v_cndmask_b32_e64 v211, v238, v211, s[18:19]
	v_sub_f32_e32 v80, v80, v239
	v_sub_f32_e32 v81, v81, v239
	v_sub_f32_e32 v82, v82, v239
	v_sub_f32_e32 v83, v83, v239
	v_sub_f32_e32 v84, v84, v239
	v_sub_f32_e32 v85, v85, v239
	v_sub_f32_e32 v86, v86, v239
	v_sub_f32_e32 v87, v87, v239
	v_cndmask_b32_e64 v80, v238, v80, s[0:1]
	v_cndmask_b32_e64 v81, v238, v81, s[6:7]
	v_cndmask_b32_e64 v82, v238, v82, s[8:9]
	v_cndmask_b32_e64 v83, v238, v83, s[10:11]
	v_cndmask_b32_e64 v84, v238, v84, s[12:13]
	v_cndmask_b32_e64 v85, v238, v85, s[14:15]
	v_cndmask_b32_e64 v86, v238, v86, s[16:17]
	v_cndmask_b32_e64 v87, v238, v87, s[18:19]
	v_sub_f32_e32 v180, v180, v239
	v_sub_f32_e32 v181, v181, v239
	v_sub_f32_e32 v182, v182, v239
	v_sub_f32_e32 v183, v183, v239
	v_sub_f32_e32 v184, v184, v239
	v_sub_f32_e32 v185, v185, v239
	v_sub_f32_e32 v186, v186, v239
	v_sub_f32_e32 v187, v187, v239
	v_cndmask_b32_e64 v180, v238, v180, s[0:1]
	v_cndmask_b32_e64 v181, v238, v181, s[6:7]
	v_cndmask_b32_e64 v182, v238, v182, s[8:9]
	v_cndmask_b32_e64 v183, v238, v183, s[10:11]
	v_cndmask_b32_e64 v184, v238, v184, s[12:13]
	v_cndmask_b32_e64 v185, v238, v185, s[14:15]
	v_cndmask_b32_e64 v186, v238, v186, s[16:17]
	v_cndmask_b32_e64 v187, v238, v187, s[18:19]
	v_sub_f32_e32 v212, v212, v239
	v_sub_f32_e32 v213, v213, v239
	v_sub_f32_e32 v214, v214, v239
	v_sub_f32_e32 v215, v215, v239
	v_sub_f32_e32 v242, v242, v239
	v_sub_f32_e32 v243, v243, v239
	v_sub_f32_e32 v244, v244, v239
	v_sub_f32_e32 v245, v245, v239
	v_cndmask_b32_e64 v212, v238, v212, s[0:1]
	v_cndmask_b32_e64 v213, v238, v213, s[6:7]
	v_cndmask_b32_e64 v214, v238, v214, s[8:9]
	v_cndmask_b32_e64 v215, v238, v215, s[10:11]
	v_cndmask_b32_e64 v242, v238, v242, s[12:13]
	v_cndmask_b32_e64 v243, v238, v243, s[14:15]
	v_cndmask_b32_e64 v244, v238, v244, s[16:17]
	v_cndmask_b32_e64 v245, v238, v245, s[18:19]
	v_add_u32_e32 v240, 0x400, v240
	s_waitcnt vmcnt(0) lgkmcnt(0)
	s_barrier
	s_cmp_eq_u32 s60, 0
	s_cbranch_scc1 .Latt_went
	s_mov_b32 s23, 0x8000
	s_mov_b32 s33, 0xa000
	v_add_u32_e32 v251, s23, v233
	v_add_u32_e32 v253, s33, v234
	ds_read_b128 v[176:179], v251 offset:0
	ds_read_b128 v[168:171], v251 offset:4096
	ds_read_b128 v[172:175], v251 offset:2048
	ds_read_b128 v[164:167], v251 offset:6144
	ds_read_b128 v[32:35], v253 offset:0
	ds_read_b128 v[28:31], v253 offset:2048
	ds_read_b128 v[24:27], v253 offset:4096
	ds_read_b128 v[20:23], v253 offset:6144
	s_waitcnt lgkmcnt(0)
	s_waitcnt vmcnt(0)
	s_cmp_gt_i32 s63, -2
	s_cbranch_scc0 .Latt_eb1
	s_barrier
.Latt_eb1:
	s_cmp_gt_i32 s63, 0
	s_cbranch_scc0 .Latt_dk2
	s_add_u32 m0, s94, s83
	s_nop 0
	buffer_load_dwordx4 v241, s[24:27], s95 offen lds
	s_add_u32 m0, s94, s77
	s_nop 0
	buffer_load_dwordx4 v255, s[40:43], s92 offen lds
	s_cmp_gt_i32 s63, 1
	s_cbranch_scc0 .Latt_dk2
	s_add_u32 s21, s95, 0x10000
	s_add_u32 s22, s92, 0x80
	s_add_u32 m0, s94, 0x18000
	s_nop 0
	buffer_load_dwordx4 v241, s[24:27], s21 offen lds
	s_add_u32 m0, s94, 0x1a000
	s_nop 0
	buffer_load_dwordx4 v255, s[40:43], s22 offen lds
.Latt_dk2:
	s_add_u32 s95, s95, 0x20000
	s_add_u32 s92, s92, 0x100
	s_sub_i32 s63, s63, 2
	s_movk_i32 s20, 0x100
	s_movk_i32 s21, 0x400
	s_bitcmp1_b32 s23, 8
	s_cselect_b32 s20, 0x3f00, s20
	s_cselect_b32 s21, 0x3c00, s21
	s_add_u32 s23, s23, s20
	s_add_u32 s33, s33, s21
	v_add_u32_e32 v251, s23, v233
	v_add_u32_e32 v253, s33, v234
	ds_read_b128 v[48:51], v251 offset:0
	ds_read_b128 v[40:43], v251 offset:4096
	ds_read_b128 v[44:47], v251 offset:2048
	ds_read_b128 v[36:39], v251 offset:6144
	ds_read_b128 v[16:19], v253 offset:0
	ds_read_b128 v[12:15], v253 offset:2048
	ds_read_b128 v[8:11], v253 offset:4096
	ds_read_b128 v[4:7], v253 offset:6144
	v_mfma_f32_16x16x32_bf16 v[188:191], v[176:179], v[132:135], v[76:79]
	v_mfma_f32_16x16x32_bf16 v[192:195], v[168:171], v[132:135], v[76:79]
	v_mfma_f32_16x16x32_bf16 v[188:191], v[172:175], v[136:139], v[188:191]
	v_mfma_f32_16x16x32_bf16 v[192:195], v[164:167], v[136:139], v[192:195]
	v_mfma_f32_16x16x32_bf16 v[196:199], v[176:179], v[140:143], v[76:79]
	v_mfma_f32_16x16x32_bf16 v[200:203], v[168:171], v[140:143], v[76:79]
	v_mfma_f32_16x16x32_bf16 v[196:199], v[172:175], v[144:147], v[196:199]
	v_mfma_f32_16x16x32_bf16 v[200:203], v[164:167], v[144:147], v[200:203]
	s_nop 2
	v_exp_f32_e32 v188, v188
	v_exp_f32_e32 v189, v189
	v_exp_f32_e32 v190, v190
	v_exp_f32_e32 v191, v191
	v_exp_f32_e32 v192, v192
	v_exp_f32_e32 v193, v193
	v_exp_f32_e32 v194, v194
	v_exp_f32_e32 v195, v195
	v_cvt_pk_bf16_f32 v246, v188, v189
	v_cvt_pk_bf16_f32 v247, v190, v191
	v_cvt_pk_bf16_f32 v248, v192, v193
	v_cvt_pk_bf16_f32 v249, v194, v195
	v_add_f32_e32 v188, v188, v189
	v_add_f32_e32 v190, v190, v191
	v_add_f32_e32 v192, v192, v193
	v_add_f32_e32 v194, v194, v195
	v_add_f32_e32 v188, v188, v190
	v_add_f32_e32 v192, v192, v194
	v_add_f32_e32 v188, v188, v192
	v_add_f32_e32 v222, v222, v188
	v_mfma_f32_16x16x32_bf16 v[188:191], v[176:179], v[148:151], v[76:79]
	v_mfma_f32_16x16x32_bf16 v[192:195], v[168:171], v[148:151], v[76:79]
	v_mfma_f32_16x16x32_bf16 v[188:191], v[172:175], v[152:155], v[188:191]
	v_mfma_f32_16x16x32_bf16 v[192:195], v[164:167], v[152:155], v[192:195]
	v_exp_f32_e32 v196, v196
	v_exp_f32_e32 v197, v197
	v_exp_f32_e32 v198, v198
	v_exp_f32_e32 v199, v199
	v_mfma_f32_16x16x32_bf16 v[96:99], v[32:35], v[246:249], v[96:99]
	v_exp_f32_e32 v200, v200
	v_exp_f32_e32 v201, v201
	v_exp_f32_e32 v202, v202
	v_exp_f32_e32 v203, v203
	v_mfma_f32_16x16x32_bf16 v[88:91], v[28:31], v[246:249], v[88:91]
	v_cvt_pk_bf16_f32 v92, v196, v197
	v_cvt_pk_bf16_f32 v93, v198, v199
	v_cvt_pk_bf16_f32 v94, v200, v201
	v_cvt_pk_bf16_f32 v95, v202, v203
	v_mfma_f32_16x16x32_bf16 v[72:75], v[24:27], v[246:249], v[72:75]
	v_add_f32_e32 v196, v196, v197
	v_add_f32_e32 v198, v198, v199
	v_add_f32_e32 v200, v200, v201
	v_add_f32_e32 v202, v202, v203
	v_mfma_f32_16x16x32_bf16 v[68:71], v[20:23], v[246:249], v[68:71]
	v_add_f32_e32 v196, v196, v198
	v_add_f32_e32 v200, v200, v202
	v_add_f32_e32 v196, v196, v200
	v_add_f32_e32 v223, v223, v196
	v_mfma_f32_16x16x32_bf16 v[196:199], v[176:179], v[156:159], v[76:79]
	v_mfma_f32_16x16x32_bf16 v[200:203], v[168:171], v[156:159], v[76:79]
	v_mfma_f32_16x16x32_bf16 v[196:199], v[172:175], v[160:163], v[196:199]
	v_mfma_f32_16x16x32_bf16 v[200:203], v[164:167], v[160:163], v[200:203]
	v_exp_f32_e32 v188, v188
	v_exp_f32_e32 v189, v189
	v_exp_f32_e32 v190, v190
	v_exp_f32_e32 v191, v191
	v_mfma_f32_16x16x32_bf16 v[64:67], v[32:35], v[92:95], v[64:67]
	v_exp_f32_e32 v192, v192
	v_exp_f32_e32 v193, v193
	v_exp_f32_e32 v194, v194
	v_exp_f32_e32 v195, v195
	v_mfma_f32_16x16x32_bf16 v[60:63], v[28:31], v[92:95], v[60:63]
	v_cvt_pk_bf16_f32 v246, v188, v189
	v_cvt_pk_bf16_f32 v247, v190, v191
	v_cvt_pk_bf16_f32 v248, v192, v193
	v_cvt_pk_bf16_f32 v249, v194, v195
	v_mfma_f32_16x16x32_bf16 v[56:59], v[24:27], v[92:95], v[56:59]
	v_add_f32_e32 v188, v188, v189
	v_add_f32_e32 v190, v190, v191
	v_add_f32_e32 v192, v192, v193
	v_add_f32_e32 v194, v194, v195
	v_mfma_f32_16x16x32_bf16 v[52:55], v[20:23], v[92:95], v[52:55]
	v_add_f32_e32 v188, v188, v190
	v_add_f32_e32 v192, v192, v194
	v_add_f32_e32 v188, v188, v192
	v_add_f32_e32 v224, v224, v188
	v_exp_f32_e32 v196, v196
	v_exp_f32_e32 v197, v197
	v_exp_f32_e32 v198, v198
	v_exp_f32_e32 v199, v199
	v_mfma_f32_16x16x32_bf16 v[128:131], v[32:35], v[246:249], v[128:131]
	v_exp_f32_e32 v200, v200
	v_exp_f32_e32 v201, v201
	v_exp_f32_e32 v202, v202
	v_exp_f32_e32 v203, v203
	v_mfma_f32_16x16x32_bf16 v[124:127], v[28:31], v[246:249], v[124:127]
	v_cvt_pk_bf16_f32 v92, v196, v197
	v_cvt_pk_bf16_f32 v93, v198, v199
	v_cvt_pk_bf16_f32 v94, v200, v201
	v_cvt_pk_bf16_f32 v95, v202, v203
	v_mfma_f32_16x16x32_bf16 v[120:123], v[24:27], v[246:249], v[120:123]
	v_add_f32_e32 v196, v196, v197
	v_add_f32_e32 v198, v198, v199
	v_add_f32_e32 v200, v200, v201
	v_add_f32_e32 v202, v202, v203
	v_mfma_f32_16x16x32_bf16 v[116:119], v[20:23], v[246:249], v[116:119]
	v_add_f32_e32 v196, v196, v198
	v_add_f32_e32 v200, v200, v202
	v_add_f32_e32 v196, v196, v200
	v_add_f32_e32 v225, v225, v196
	v_mfma_f32_16x16x32_bf16 v[112:115], v[32:35], v[92:95], v[112:115]
	v_mfma_f32_16x16x32_bf16 v[108:111], v[28:31], v[92:95], v[108:111]
	v_mfma_f32_16x16x32_bf16 v[104:107], v[24:27], v[92:95], v[104:107]
	v_mfma_f32_16x16x32_bf16 v[100:103], v[20:23], v[92:95], v[100:103]
	s_waitcnt lgkmcnt(0)
	s_movk_i32 s20, 0x100
	s_movk_i32 s21, 0x400
	s_bitcmp1_b32 s23, 8
	s_cselect_b32 s20, 0x3f00, s20
	s_cselect_b32 s21, 0x3c00, s21
	s_add_u32 s23, s23, s20
	s_add_u32 s33, s33, s21
	v_add_u32_e32 v251, s23, v233
	v_add_u32_e32 v253, s33, v234
	ds_read_b128 v[176:179], v251 offset:0
	ds_read_b128 v[168:171], v251 offset:4096
	ds_read_b128 v[172:175], v251 offset:2048
	ds_read_b128 v[164:167], v251 offset:6144
	ds_read_b128 v[32:35], v253 offset:0
	ds_read_b128 v[28:31], v253 offset:2048
	ds_read_b128 v[24:27], v253 offset:4096
	ds_read_b128 v[20:23], v253 offset:6144
	v_mfma_f32_16x16x32_bf16 v[188:191], v[48:51], v[132:135], v[76:79]
	v_mfma_f32_16x16x32_bf16 v[192:195], v[40:43], v[132:135], v[76:79]
	v_mfma_f32_16x16x32_bf16 v[188:191], v[44:47], v[136:139], v[188:191]
	v_mfma_f32_16x16x32_bf16 v[192:195], v[36:39], v[136:139], v[192:195]
	v_mfma_f32_16x16x32_bf16 v[196:199], v[48:51], v[140:143], v[76:79]
	v_mfma_f32_16x16x32_bf16 v[200:203], v[40:43], v[140:143], v[76:79]
	v_mfma_f32_16x16x32_bf16 v[196:199], v[44:47], v[144:147], v[196:199]
	v_mfma_f32_16x16x32_bf16 v[200:203], v[36:39], v[144:147], v[200:203]
	s_nop 2
	v_exp_f32_e32 v188, v188
	v_exp_f32_e32 v189, v189
	v_exp_f32_e32 v190, v190
	v_exp_f32_e32 v191, v191
	v_exp_f32_e32 v192, v192
	v_exp_f32_e32 v193, v193
	v_exp_f32_e32 v194, v194
	v_exp_f32_e32 v195, v195
	v_cvt_pk_bf16_f32 v246, v188, v189
	v_cvt_pk_bf16_f32 v247, v190, v191
	v_cvt_pk_bf16_f32 v248, v192, v193
	v_cvt_pk_bf16_f32 v249, v194, v195
	v_add_f32_e32 v188, v188, v189
	v_add_f32_e32 v190, v190, v191
	v_add_f32_e32 v192, v192, v193
	v_add_f32_e32 v194, v194, v195
	v_add_f32_e32 v188, v188, v190
	v_add_f32_e32 v192, v192, v194
	v_add_f32_e32 v188, v188, v192
	v_add_f32_e32 v222, v222, v188
	v_mfma_f32_16x16x32_bf16 v[188:191], v[48:51], v[148:151], v[76:79]
	v_mfma_f32_16x16x32_bf16 v[192:195], v[40:43], v[148:151], v[76:79]
	v_mfma_f32_16x16x32_bf16 v[188:191], v[44:47], v[152:155], v[188:191]
	v_mfma_f32_16x16x32_bf16 v[192:195], v[36:39], v[152:155], v[192:195]
	v_exp_f32_e32 v196, v196
	v_exp_f32_e32 v197, v197
	v_exp_f32_e32 v198, v198
	v_exp_f32_e32 v199, v199
	v_mfma_f32_16x16x32_bf16 v[96:99], v[16:19], v[246:249], v[96:99]
	v_exp_f32_e32 v200, v200
	v_exp_f32_e32 v201, v201
	v_exp_f32_e32 v202, v202
	v_exp_f32_e32 v203, v203
	v_mfma_f32_16x16x32_bf16 v[88:91], v[12:15], v[246:249], v[88:91]
	v_cvt_pk_bf16_f32 v92, v196, v197
	v_cvt_pk_bf16_f32 v93, v198, v199
	v_cvt_pk_bf16_f32 v94, v200, v201
	v_cvt_pk_bf16_f32 v95, v202, v203
	v_mfma_f32_16x16x32_bf16 v[72:75], v[8:11], v[246:249], v[72:75]
	v_add_f32_e32 v196, v196, v197
	v_add_f32_e32 v198, v198, v199
	v_add_f32_e32 v200, v200, v201
	v_add_f32_e32 v202, v202, v203
	v_mfma_f32_16x16x32_bf16 v[68:71], v[4:7], v[246:249], v[68:71]
	v_add_f32_e32 v196, v196, v198
	v_add_f32_e32 v200, v200, v202
	v_add_f32_e32 v196, v196, v200
	v_add_f32_e32 v223, v223, v196
	v_mfma_f32_16x16x32_bf16 v[196:199], v[48:51], v[156:159], v[76:79]
	v_mfma_f32_16x16x32_bf16 v[200:203], v[40:43], v[156:159], v[76:79]
	v_mfma_f32_16x16x32_bf16 v[196:199], v[44:47], v[160:163], v[196:199]
	v_mfma_f32_16x16x32_bf16 v[200:203], v[36:39], v[160:163], v[200:203]
	v_exp_f32_e32 v188, v188
	v_exp_f32_e32 v189, v189
	v_exp_f32_e32 v190, v190
	v_exp_f32_e32 v191, v191
	v_mfma_f32_16x16x32_bf16 v[64:67], v[16:19], v[92:95], v[64:67]
	v_exp_f32_e32 v192, v192
	v_exp_f32_e32 v193, v193
	v_exp_f32_e32 v194, v194
	v_exp_f32_e32 v195, v195
	v_mfma_f32_16x16x32_bf16 v[60:63], v[12:15], v[92:95], v[60:63]
	v_cvt_pk_bf16_f32 v246, v188, v189
	v_cvt_pk_bf16_f32 v247, v190, v191
	v_cvt_pk_bf16_f32 v248, v192, v193
	v_cvt_pk_bf16_f32 v249, v194, v195
	v_mfma_f32_16x16x32_bf16 v[56:59], v[8:11], v[92:95], v[56:59]
	v_add_f32_e32 v188, v188, v189
	v_add_f32_e32 v190, v190, v191
	v_add_f32_e32 v192, v192, v193
	v_add_f32_e32 v194, v194, v195
	v_mfma_f32_16x16x32_bf16 v[52:55], v[4:7], v[92:95], v[52:55]
	v_add_f32_e32 v188, v188, v190
	v_add_f32_e32 v192, v192, v194
	v_add_f32_e32 v188, v188, v192
	v_add_f32_e32 v224, v224, v188
	v_exp_f32_e32 v196, v196
	v_exp_f32_e32 v197, v197
	v_exp_f32_e32 v198, v198
	v_exp_f32_e32 v199, v199
	v_mfma_f32_16x16x32_bf16 v[128:131], v[16:19], v[246:249], v[128:131]
	v_exp_f32_e32 v200, v200
	v_exp_f32_e32 v201, v201
	v_exp_f32_e32 v202, v202
	v_exp_f32_e32 v203, v203
	v_mfma_f32_16x16x32_bf16 v[124:127], v[12:15], v[246:249], v[124:127]
	v_cvt_pk_bf16_f32 v92, v196, v197
	v_cvt_pk_bf16_f32 v93, v198, v199
	v_cvt_pk_bf16_f32 v94, v200, v201
	v_cvt_pk_bf16_f32 v95, v202, v203
	v_mfma_f32_16x16x32_bf16 v[120:123], v[8:11], v[246:249], v[120:123]
	v_add_f32_e32 v196, v196, v197
	v_add_f32_e32 v198, v198, v199
	v_add_f32_e32 v200, v200, v201
	v_add_f32_e32 v202, v202, v203
	v_mfma_f32_16x16x32_bf16 v[116:119], v[4:7], v[246:249], v[116:119]
	v_add_f32_e32 v196, v196, v198
	v_add_f32_e32 v200, v200, v202
	v_add_f32_e32 v196, v196, v200
	v_add_f32_e32 v225, v225, v196
	v_mfma_f32_16x16x32_bf16 v[112:115], v[16:19], v[92:95], v[112:115]
	v_mfma_f32_16x16x32_bf16 v[108:111], v[12:15], v[92:95], v[108:111]
	v_mfma_f32_16x16x32_bf16 v[104:107], v[8:11], v[92:95], v[104:107]
	v_mfma_f32_16x16x32_bf16 v[100:103], v[4:7], v[92:95], v[100:103]
	s_waitcnt lgkmcnt(0)
	s_waitcnt vmcnt(0)
	s_cmp_gt_i32 s63, -2
	s_cbranch_scc0 .Latt_eb3
	s_barrier
.Latt_eb3:
	s_cmp_gt_i32 s63, 0
	s_cbranch_scc0 .Latt_dk4
	s_add_u32 m0, s94, 0x1c000
	s_nop 0
	buffer_load_dwordx4 v241, s[24:27], s95 offen lds
	s_add_u32 m0, s94, 0x1e000
	s_nop 0
	buffer_load_dwordx4 v255, s[40:43], s92 offen lds
	s_cmp_gt_i32 s63, 1
	s_cbranch_scc0 .Latt_dk4
	s_add_u32 s21, s95, 0x10000
	s_add_u32 s22, s92, 0x80
	s_add_u32 m0, s94, 0x20010
	s_nop 0
	buffer_load_dwordx4 v241, s[24:27], s21 offen lds
	s_add_u32 m0, s94, 0x22010
	s_nop 0
	buffer_load_dwordx4 v255, s[40:43], s22 offen lds
.Latt_dk4:
	s_add_u32 s95, s95, 0x20000
	s_add_u32 s92, s92, 0x100
	s_sub_i32 s63, s63, 2
	s_movk_i32 s20, 0x100
	s_movk_i32 s21, 0x400
	s_bitcmp1_b32 s23, 8
	s_cselect_b32 s20, 0x3f00, s20
	s_cselect_b32 s21, 0x3c00, s21
	s_add_u32 s23, s23, s20
	s_add_u32 s33, s33, s21
	v_add_u32_e32 v251, s23, v233
	v_add_u32_e32 v253, s33, v234
	ds_read_b128 v[48:51], v251 offset:0
	ds_read_b128 v[40:43], v251 offset:4096
	ds_read_b128 v[44:47], v251 offset:2048
	ds_read_b128 v[36:39], v251 offset:6144
	ds_read_b128 v[16:19], v253 offset:0
	ds_read_b128 v[12:15], v253 offset:2048
	ds_read_b128 v[8:11], v253 offset:4096
	ds_read_b128 v[4:7], v253 offset:6144
	v_mfma_f32_16x16x32_bf16 v[188:191], v[176:179], v[132:135], v[76:79]
	v_mfma_f32_16x16x32_bf16 v[192:195], v[168:171], v[132:135], v[76:79]
	v_mfma_f32_16x16x32_bf16 v[188:191], v[172:175], v[136:139], v[188:191]
	v_mfma_f32_16x16x32_bf16 v[192:195], v[164:167], v[136:139], v[192:195]
	v_mfma_f32_16x16x32_bf16 v[196:199], v[176:179], v[140:143], v[76:79]
	v_mfma_f32_16x16x32_bf16 v[200:203], v[168:171], v[140:143], v[76:79]
	v_mfma_f32_16x16x32_bf16 v[196:199], v[172:175], v[144:147], v[196:199]
	v_mfma_f32_16x16x32_bf16 v[200:203], v[164:167], v[144:147], v[200:203]
	s_nop 2
	v_exp_f32_e32 v188, v188
	v_exp_f32_e32 v189, v189
	v_exp_f32_e32 v190, v190
	v_exp_f32_e32 v191, v191
	v_exp_f32_e32 v192, v192
	v_exp_f32_e32 v193, v193
	v_exp_f32_e32 v194, v194
	v_exp_f32_e32 v195, v195
	v_cvt_pk_bf16_f32 v246, v188, v189
	v_cvt_pk_bf16_f32 v247, v190, v191
	v_cvt_pk_bf16_f32 v248, v192, v193
	v_cvt_pk_bf16_f32 v249, v194, v195
	v_add_f32_e32 v188, v188, v189
	v_add_f32_e32 v190, v190, v191
	v_add_f32_e32 v192, v192, v193
	v_add_f32_e32 v194, v194, v195
	v_add_f32_e32 v188, v188, v190
	v_add_f32_e32 v192, v192, v194
	v_add_f32_e32 v188, v188, v192
	v_add_f32_e32 v222, v222, v188
	v_mfma_f32_16x16x32_bf16 v[188:191], v[176:179], v[148:151], v[76:79]
	v_mfma_f32_16x16x32_bf16 v[192:195], v[168:171], v[148:151], v[76:79]
	v_mfma_f32_16x16x32_bf16 v[188:191], v[172:175], v[152:155], v[188:191]
	v_mfma_f32_16x16x32_bf16 v[192:195], v[164:167], v[152:155], v[192:195]
	v_exp_f32_e32 v196, v196
	v_exp_f32_e32 v197, v197
	v_exp_f32_e32 v198, v198
	v_exp_f32_e32 v199, v199
	v_mfma_f32_16x16x32_bf16 v[96:99], v[32:35], v[246:249], v[96:99]
	v_exp_f32_e32 v200, v200
	v_exp_f32_e32 v201, v201
	v_exp_f32_e32 v202, v202
	v_exp_f32_e32 v203, v203
	v_mfma_f32_16x16x32_bf16 v[88:91], v[28:31], v[246:249], v[88:91]
	v_cvt_pk_bf16_f32 v92, v196, v197
	v_cvt_pk_bf16_f32 v93, v198, v199
	v_cvt_pk_bf16_f32 v94, v200, v201
	v_cvt_pk_bf16_f32 v95, v202, v203
	v_mfma_f32_16x16x32_bf16 v[72:75], v[24:27], v[246:249], v[72:75]
	v_add_f32_e32 v196, v196, v197
	v_add_f32_e32 v198, v198, v199
	v_add_f32_e32 v200, v200, v201
	v_add_f32_e32 v202, v202, v203
	v_mfma_f32_16x16x32_bf16 v[68:71], v[20:23], v[246:249], v[68:71]
	v_add_f32_e32 v196, v196, v198
	v_add_f32_e32 v200, v200, v202
	v_add_f32_e32 v196, v196, v200
	v_add_f32_e32 v223, v223, v196
	v_mfma_f32_16x16x32_bf16 v[196:199], v[176:179], v[156:159], v[76:79]
	v_mfma_f32_16x16x32_bf16 v[200:203], v[168:171], v[156:159], v[76:79]
	v_mfma_f32_16x16x32_bf16 v[196:199], v[172:175], v[160:163], v[196:199]
	v_mfma_f32_16x16x32_bf16 v[200:203], v[164:167], v[160:163], v[200:203]
	v_exp_f32_e32 v188, v188
	v_exp_f32_e32 v189, v189
	v_exp_f32_e32 v190, v190
	v_exp_f32_e32 v191, v191
	v_mfma_f32_16x16x32_bf16 v[64:67], v[32:35], v[92:95], v[64:67]
	v_exp_f32_e32 v192, v192
	v_exp_f32_e32 v193, v193
	v_exp_f32_e32 v194, v194
	v_exp_f32_e32 v195, v195
	v_mfma_f32_16x16x32_bf16 v[60:63], v[28:31], v[92:95], v[60:63]
	v_cvt_pk_bf16_f32 v246, v188, v189
	v_cvt_pk_bf16_f32 v247, v190, v191
	v_cvt_pk_bf16_f32 v248, v192, v193
	v_cvt_pk_bf16_f32 v249, v194, v195
	v_mfma_f32_16x16x32_bf16 v[56:59], v[24:27], v[92:95], v[56:59]
	v_add_f32_e32 v188, v188, v189
	v_add_f32_e32 v190, v190, v191
	v_add_f32_e32 v192, v192, v193
	v_add_f32_e32 v194, v194, v195
	v_mfma_f32_16x16x32_bf16 v[52:55], v[20:23], v[92:95], v[52:55]
	v_add_f32_e32 v188, v188, v190
	v_add_f32_e32 v192, v192, v194
	v_add_f32_e32 v188, v188, v192
	v_add_f32_e32 v224, v224, v188
	v_exp_f32_e32 v196, v196
	v_exp_f32_e32 v197, v197
	v_exp_f32_e32 v198, v198
	v_exp_f32_e32 v199, v199
	v_mfma_f32_16x16x32_bf16 v[128:131], v[32:35], v[246:249], v[128:131]
	v_exp_f32_e32 v200, v200
	v_exp_f32_e32 v201, v201
	v_exp_f32_e32 v202, v202
	v_exp_f32_e32 v203, v203
	v_mfma_f32_16x16x32_bf16 v[124:127], v[28:31], v[246:249], v[124:127]
	v_cvt_pk_bf16_f32 v92, v196, v197
	v_cvt_pk_bf16_f32 v93, v198, v199
	v_cvt_pk_bf16_f32 v94, v200, v201
	v_cvt_pk_bf16_f32 v95, v202, v203
	v_mfma_f32_16x16x32_bf16 v[120:123], v[24:27], v[246:249], v[120:123]
	v_add_f32_e32 v196, v196, v197
	v_add_f32_e32 v198, v198, v199
	v_add_f32_e32 v200, v200, v201
	v_add_f32_e32 v202, v202, v203
	v_mfma_f32_16x16x32_bf16 v[116:119], v[20:23], v[246:249], v[116:119]
	v_add_f32_e32 v196, v196, v198
	v_add_f32_e32 v200, v200, v202
	v_add_f32_e32 v196, v196, v200
	v_add_f32_e32 v225, v225, v196
	v_mfma_f32_16x16x32_bf16 v[112:115], v[32:35], v[92:95], v[112:115]
	v_mfma_f32_16x16x32_bf16 v[108:111], v[28:31], v[92:95], v[108:111]
	v_mfma_f32_16x16x32_bf16 v[104:107], v[24:27], v[92:95], v[104:107]
	v_mfma_f32_16x16x32_bf16 v[100:103], v[20:23], v[92:95], v[100:103]
	s_waitcnt lgkmcnt(0)
	ds_read_b128 v[176:179], v1 offset:0
	ds_read_b128 v[168:171], v1 offset:4096
	ds_read_b128 v[172:175], v1 offset:2048
	ds_read_b128 v[164:167], v1 offset:6144
	ds_read_b128 v[32:35], v221 offset:0
	ds_read_b128 v[28:31], v221 offset:2048
	ds_read_b128 v[24:27], v221 offset:4096
	ds_read_b128 v[20:23], v221 offset:6144
	v_mfma_f32_16x16x32_bf16 v[188:191], v[48:51], v[132:135], v[76:79]
	v_mfma_f32_16x16x32_bf16 v[192:195], v[40:43], v[132:135], v[76:79]
	v_mfma_f32_16x16x32_bf16 v[188:191], v[44:47], v[136:139], v[188:191]
	v_mfma_f32_16x16x32_bf16 v[192:195], v[36:39], v[136:139], v[192:195]
	v_mfma_f32_16x16x32_bf16 v[196:199], v[48:51], v[140:143], v[76:79]
	v_mfma_f32_16x16x32_bf16 v[200:203], v[40:43], v[140:143], v[76:79]
	v_mfma_f32_16x16x32_bf16 v[196:199], v[44:47], v[144:147], v[196:199]
	v_mfma_f32_16x16x32_bf16 v[200:203], v[36:39], v[144:147], v[200:203]
	s_nop 2
	v_exp_f32_e32 v188, v188
	v_exp_f32_e32 v189, v189
	v_exp_f32_e32 v190, v190
	v_exp_f32_e32 v191, v191
	v_exp_f32_e32 v192, v192
	v_exp_f32_e32 v193, v193
	v_exp_f32_e32 v194, v194
	v_exp_f32_e32 v195, v195
	v_cvt_pk_bf16_f32 v246, v188, v189
	v_cvt_pk_bf16_f32 v247, v190, v191
	v_cvt_pk_bf16_f32 v248, v192, v193
	v_cvt_pk_bf16_f32 v249, v194, v195
	v_add_f32_e32 v188, v188, v189
	v_add_f32_e32 v190, v190, v191
	v_add_f32_e32 v192, v192, v193
	v_add_f32_e32 v194, v194, v195
	v_add_f32_e32 v188, v188, v190
	v_add_f32_e32 v192, v192, v194
	v_add_f32_e32 v188, v188, v192
	v_add_f32_e32 v222, v222, v188
	v_mfma_f32_16x16x32_bf16 v[188:191], v[48:51], v[148:151], v[76:79]
	v_mfma_f32_16x16x32_bf16 v[192:195], v[40:43], v[148:151], v[76:79]
	v_mfma_f32_16x16x32_bf16 v[188:191], v[44:47], v[152:155], v[188:191]
	v_mfma_f32_16x16x32_bf16 v[192:195], v[36:39], v[152:155], v[192:195]
	v_exp_f32_e32 v196, v196
	v_exp_f32_e32 v197, v197
	v_exp_f32_e32 v198, v198
	v_exp_f32_e32 v199, v199
	v_mfma_f32_16x16x32_bf16 v[96:99], v[16:19], v[246:249], v[96:99]
	v_exp_f32_e32 v200, v200
	v_exp_f32_e32 v201, v201
	v_exp_f32_e32 v202, v202
	v_exp_f32_e32 v203, v203
	v_mfma_f32_16x16x32_bf16 v[88:91], v[12:15], v[246:249], v[88:91]
	v_cvt_pk_bf16_f32 v92, v196, v197
	v_cvt_pk_bf16_f32 v93, v198, v199
	v_cvt_pk_bf16_f32 v94, v200, v201
	v_cvt_pk_bf16_f32 v95, v202, v203
	v_mfma_f32_16x16x32_bf16 v[72:75], v[8:11], v[246:249], v[72:75]
	v_add_f32_e32 v196, v196, v197
	v_add_f32_e32 v198, v198, v199
	v_add_f32_e32 v200, v200, v201
	v_add_f32_e32 v202, v202, v203
	v_mfma_f32_16x16x32_bf16 v[68:71], v[4:7], v[246:249], v[68:71]
	v_add_f32_e32 v196, v196, v198
	v_add_f32_e32 v200, v200, v202
	v_add_f32_e32 v196, v196, v200
	v_add_f32_e32 v223, v223, v196
	v_mfma_f32_16x16x32_bf16 v[196:199], v[48:51], v[156:159], v[76:79]
	v_mfma_f32_16x16x32_bf16 v[200:203], v[40:43], v[156:159], v[76:79]
	v_mfma_f32_16x16x32_bf16 v[196:199], v[44:47], v[160:163], v[196:199]
	v_mfma_f32_16x16x32_bf16 v[200:203], v[36:39], v[160:163], v[200:203]
	v_exp_f32_e32 v188, v188
	v_exp_f32_e32 v189, v189
	v_exp_f32_e32 v190, v190
	v_exp_f32_e32 v191, v191
	v_mfma_f32_16x16x32_bf16 v[64:67], v[16:19], v[92:95], v[64:67]
	v_exp_f32_e32 v192, v192
	v_exp_f32_e32 v193, v193
	v_exp_f32_e32 v194, v194
	v_exp_f32_e32 v195, v195
	v_mfma_f32_16x16x32_bf16 v[60:63], v[12:15], v[92:95], v[60:63]
	v_cvt_pk_bf16_f32 v246, v188, v189
	v_cvt_pk_bf16_f32 v247, v190, v191
	v_cvt_pk_bf16_f32 v248, v192, v193
	v_cvt_pk_bf16_f32 v249, v194, v195
	v_mfma_f32_16x16x32_bf16 v[56:59], v[8:11], v[92:95], v[56:59]
	v_add_f32_e32 v188, v188, v189
	v_add_f32_e32 v190, v190, v191
	v_add_f32_e32 v192, v192, v193
	v_add_f32_e32 v194, v194, v195
	v_mfma_f32_16x16x32_bf16 v[52:55], v[4:7], v[92:95], v[52:55]
	v_add_f32_e32 v188, v188, v190
	v_add_f32_e32 v192, v192, v194
	v_add_f32_e32 v188, v188, v192
	v_add_f32_e32 v224, v224, v188
	v_exp_f32_e32 v196, v196
	v_exp_f32_e32 v197, v197
	v_exp_f32_e32 v198, v198
	v_exp_f32_e32 v199, v199
	v_mfma_f32_16x16x32_bf16 v[128:131], v[16:19], v[246:249], v[128:131]
	v_exp_f32_e32 v200, v200
	v_exp_f32_e32 v201, v201
	v_exp_f32_e32 v202, v202
	v_exp_f32_e32 v203, v203
	v_mfma_f32_16x16x32_bf16 v[124:127], v[12:15], v[246:249], v[124:127]
	v_cvt_pk_bf16_f32 v92, v196, v197
	v_cvt_pk_bf16_f32 v93, v198, v199
	v_cvt_pk_bf16_f32 v94, v200, v201
	v_cvt_pk_bf16_f32 v95, v202, v203
	v_mfma_f32_16x16x32_bf16 v[120:123], v[8:11], v[246:249], v[120:123]
	v_add_f32_e32 v196, v196, v197
	v_add_f32_e32 v198, v198, v199
	v_add_f32_e32 v200, v200, v201
	v_add_f32_e32 v202, v202, v203
	v_mfma_f32_16x16x32_bf16 v[116:119], v[4:7], v[246:249], v[116:119]
	v_add_f32_e32 v196, v196, v198
	v_add_f32_e32 v200, v200, v202
	v_add_f32_e32 v196, v196, v200
	v_add_f32_e32 v225, v225, v196
	v_mfma_f32_16x16x32_bf16 v[112:115], v[16:19], v[92:95], v[112:115]
	v_mfma_f32_16x16x32_bf16 v[108:111], v[12:15], v[92:95], v[108:111]
	v_mfma_f32_16x16x32_bf16 v[104:107], v[8:11], v[92:95], v[104:107]
	v_mfma_f32_16x16x32_bf16 v[100:103], v[4:7], v[92:95], v[100:103]
	s_nop 7
	s_branch .Latt_wgo
.Latt_went:
	ds_read_b128 v[176:179], v1 offset:0
	ds_read_b128 v[168:171], v1 offset:4096
	ds_read_b128 v[172:175], v1 offset:2048
	ds_read_b128 v[164:167], v1 offset:6144
	ds_read_b128 v[32:35], v221 offset:0
	ds_read_b128 v[28:31], v221 offset:2048
	ds_read_b128 v[24:27], v221 offset:4096
	ds_read_b128 v[20:23], v221 offset:6144
.Latt_wgo:
	s_cmp_eq_u32 s76, 8
	s_cbranch_scc1 .Latt_n8
	s_waitcnt lgkmcnt(0)
	s_waitcnt vmcnt(0)
	s_cmp_gt_i32 s63, -2
	s_cbranch_scc0 .Latt_eb5
	s_barrier

.Latt_dk6:
	s_add_u32 s95, s95, 0x20000
	s_add_u32 s92, s92, 0x100
	s_sub_i32 s63, s63, 2
	ds_read_b128 v[48:51], v2 offset:0
	ds_read_b128 v[40:43], v2 offset:4096
	ds_read_b128 v[44:47], v2 offset:2048
	ds_read_b128 v[36:39], v2 offset:6144
	ds_read_b128 v[16:19], v235 offset:0
	ds_read_b128 v[12:15], v235 offset:2048
	ds_read_b128 v[8:11], v235 offset:4096
	ds_read_b128 v[4:7], v235 offset:6144
	ds_read2_b32 v[212:213], v240 offset0:0 offset1:1
	ds_read2_b32 v[214:215], v240 offset0:2 offset1:3
	ds_read2_b32 v[242:243], v240 offset0:4 offset1:5
	ds_read2_b32 v[244:245], v240 offset0:6 offset1:7
	v_mfma_f32_16x16x32_bf16 v[188:191], v[176:179], v[132:135], v[204:207]
	v_mfma_f32_16x16x32_bf16 v[192:195], v[168:171], v[132:135], v[208:211]
	v_mfma_f32_16x16x32_bf16 v[188:191], v[172:175], v[136:139], v[188:191]
	v_mfma_f32_16x16x32_bf16 v[192:195], v[164:167], v[136:139], v[192:195]
	s_nop 6
	v_exp_f32_e32 v188, v188
	v_exp_f32_e32 v189, v189
	v_exp_f32_e32 v190, v190
	v_exp_f32_e32 v191, v191
	v_exp_f32_e32 v192, v192
	v_exp_f32_e32 v193, v193
	v_exp_f32_e32 v194, v194
	v_exp_f32_e32 v195, v195
	v_cvt_pk_bf16_f32 v246, v188, v189
	v_cvt_pk_bf16_f32 v247, v190, v191
	v_cvt_pk_bf16_f32 v248, v192, v193
	v_cvt_pk_bf16_f32 v249, v194, v195
	v_add_f32_e32 v188, v188, v189
	v_add_f32_e32 v190, v190, v191
	v_add_f32_e32 v192, v192, v193
	v_add_f32_e32 v194, v194, v195
	v_add_f32_e32 v188, v188, v190
	v_add_f32_e32 v192, v192, v194
	v_add_f32_e32 v188, v188, v192
	v_add_f32_e32 v222, v222, v188
	s_waitcnt lgkmcnt(0)
	v_sub_f32_e32 v212, v212, v239
	v_sub_f32_e32 v213, v213, v239
	v_sub_f32_e32 v214, v214, v239
	v_mfma_f32_16x16x32_bf16 v[96:99], v[32:35], v[246:249], v[96:99]
	v_sub_f32_e32 v215, v215, v239
	v_sub_f32_e32 v242, v242, v239
	v_sub_f32_e32 v243, v243, v239
	v_mfma_f32_16x16x32_bf16 v[88:91], v[28:31], v[246:249], v[88:91]
	v_sub_f32_e32 v244, v244, v239
	v_sub_f32_e32 v245, v245, v239
	v_cndmask_b32_e64 v212, v238, v212, s[0:1]
	v_mfma_f32_16x16x32_bf16 v[72:75], v[24:27], v[246:249], v[72:75]
	v_cndmask_b32_e64 v213, v238, v213, s[6:7]
	v_cndmask_b32_e64 v214, v238, v214, s[8:9]
	v_cndmask_b32_e64 v215, v238, v215, s[10:11]
	v_mfma_f32_16x16x32_bf16 v[68:71], v[20:23], v[246:249], v[68:71]
	v_cndmask_b32_e64 v242, v238, v242, s[12:13]
	v_cndmask_b32_e64 v243, v238, v243, s[14:15]
	v_cndmask_b32_e64 v244, v238, v244, s[16:17]
	v_cndmask_b32_e64 v245, v238, v245, s[18:19]
	v_add_u32_e32 v240, 0x100, v240
	s_waitcnt lgkmcnt(0)
	ds_read_b128 v[176:179], v3 offset:0
	ds_read_b128 v[168:171], v3 offset:4096
	ds_read_b128 v[172:175], v3 offset:2048
	ds_read_b128 v[164:167], v3 offset:6144
	ds_read_b128 v[32:35], v250 offset:0
	ds_read_b128 v[28:31], v250 offset:2048
	ds_read_b128 v[24:27], v250 offset:4096
	ds_read_b128 v[20:23], v250 offset:6144
	ds_read2_b32 v[180:181], v240 offset0:0 offset1:1
	ds_read2_b32 v[182:183], v240 offset0:2 offset1:3
	ds_read2_b32 v[184:185], v240 offset0:4 offset1:5
	ds_read2_b32 v[186:187], v240 offset0:6 offset1:7
	v_mfma_f32_16x16x32_bf16 v[188:191], v[48:51], v[140:143], v[204:207]
	v_mfma_f32_16x16x32_bf16 v[192:195], v[40:43], v[140:143], v[208:211]
	v_mfma_f32_16x16x32_bf16 v[188:191], v[44:47], v[144:147], v[188:191]
	v_mfma_f32_16x16x32_bf16 v[192:195], v[36:39], v[144:147], v[192:195]
	v_mfma_f32_16x16x32_bf16 v[196:199], v[48:51], v[132:135], v[212:215]
	v_mfma_f32_16x16x32_bf16 v[200:203], v[40:43], v[132:135], v[242:245]
	v_mfma_f32_16x16x32_bf16 v[196:199], v[44:47], v[136:139], v[196:199]
	v_mfma_f32_16x16x32_bf16 v[200:203], v[36:39], v[136:139], v[200:203]
	s_nop 2
	v_exp_f32_e32 v188, v188
	v_exp_f32_e32 v189, v189
	v_exp_f32_e32 v190, v190
	v_exp_f32_e32 v191, v191
	v_exp_f32_e32 v192, v192
	v_exp_f32_e32 v193, v193
	v_exp_f32_e32 v194, v194
	v_exp_f32_e32 v195, v195
	v_cvt_pk_bf16_f32 v246, v188, v189
	v_cvt_pk_bf16_f32 v247, v190, v191
	v_cvt_pk_bf16_f32 v248, v192, v193
	v_cvt_pk_bf16_f32 v249, v194, v195
	v_add_f32_e32 v188, v188, v189
	v_add_f32_e32 v190, v190, v191
	v_add_f32_e32 v192, v192, v193
	v_add_f32_e32 v194, v194, v195
	v_add_f32_e32 v188, v188, v190
	v_add_f32_e32 v192, v192, v194
	v_add_f32_e32 v188, v188, v192
	v_add_f32_e32 v223, v223, v188
	v_exp_f32_e32 v196, v196
	v_exp_f32_e32 v197, v197
	v_exp_f32_e32 v198, v198
	v_exp_f32_e32 v199, v199
	v_mfma_f32_16x16x32_bf16 v[64:67], v[16:19], v[246:249], v[64:67]
	v_exp_f32_e32 v200, v200
	v_exp_f32_e32 v201, v201
	v_exp_f32_e32 v202, v202
	v_exp_f32_e32 v203, v203
	v_mfma_f32_16x16x32_bf16 v[60:63], v[12:15], v[246:249], v[60:63]
	v_cvt_pk_bf16_f32 v92, v196, v197
	v_cvt_pk_bf16_f32 v93, v198, v199
	v_cvt_pk_bf16_f32 v94, v200, v201
	v_cvt_pk_bf16_f32 v95, v202, v203
	v_mfma_f32_16x16x32_bf16 v[56:59], v[8:11], v[246:249], v[56:59]
	v_add_f32_e32 v196, v196, v197
	v_add_f32_e32 v198, v198, v199
	v_add_f32_e32 v200, v200, v201
	v_add_f32_e32 v202, v202, v203
	v_mfma_f32_16x16x32_bf16 v[52:55], v[4:7], v[246:249], v[52:55]
	v_add_f32_e32 v196, v196, v198
	v_add_f32_e32 v200, v200, v202
	v_add_f32_e32 v196, v196, v200
	v_add_f32_e32 v222, v222, v196
	s_waitcnt lgkmcnt(0)
	v_sub_f32_e32 v180, v180, v239
	v_sub_f32_e32 v181, v181, v239
	v_sub_f32_e32 v182, v182, v239
	v_mfma_f32_16x16x32_bf16 v[96:99], v[16:19], v[92:95], v[96:99]
	v_sub_f32_e32 v183, v183, v239
	v_sub_f32_e32 v184, v184, v239
	v_sub_f32_e32 v185, v185, v239
	v_mfma_f32_16x16x32_bf16 v[88:91], v[12:15], v[92:95], v[88:91]
	v_sub_f32_e32 v186, v186, v239
	v_sub_f32_e32 v187, v187, v239
	v_cndmask_b32_e64 v180, v238, v180, s[0:1]
	v_mfma_f32_16x16x32_bf16 v[72:75], v[8:11], v[92:95], v[72:75]
	v_cndmask_b32_e64 v181, v238, v181, s[6:7]
	v_cndmask_b32_e64 v182, v238, v182, s[8:9]
	v_cndmask_b32_e64 v183, v238, v183, s[10:11]
	v_mfma_f32_16x16x32_bf16 v[68:71], v[4:7], v[92:95], v[68:71]
	v_cndmask_b32_e64 v184, v238, v184, s[12:13]
	v_cndmask_b32_e64 v185, v238, v185, s[14:15]
	v_cndmask_b32_e64 v186, v238, v186, s[16:17]
	v_cndmask_b32_e64 v187, v238, v187, s[18:19]
	v_add_u32_e32 v240, 0x100, v240
	s_waitcnt lgkmcnt(0)
	s_waitcnt vmcnt(0)
	s_cmp_gt_i32 s63, -2
	s_cbranch_scc0 .Latt_eb7
	s_barrier

.Latt_dk8:
	s_add_u32 s95, s95, 0x20000
	s_add_u32 s92, s92, 0x100
	s_sub_i32 s63, s63, 2
	ds_read_b128 v[48:51], v220 offset:0
	ds_read_b128 v[40:43], v220 offset:4096
	ds_read_b128 v[44:47], v220 offset:2048
	ds_read_b128 v[36:39], v220 offset:6144
	ds_read_b128 v[16:19], v254 offset:0
	ds_read_b128 v[12:15], v254 offset:2048
	ds_read_b128 v[8:11], v254 offset:4096
	ds_read_b128 v[4:7], v254 offset:6144
	ds_read2_b32 v[80:81], v240 offset0:0 offset1:1
	ds_read2_b32 v[82:83], v240 offset0:2 offset1:3
	ds_read2_b32 v[84:85], v240 offset0:4 offset1:5
	ds_read2_b32 v[86:87], v240 offset0:6 offset1:7
	v_mfma_f32_16x16x32_bf16 v[188:191], v[176:179], v[148:151], v[204:207]
	v_mfma_f32_16x16x32_bf16 v[192:195], v[168:171], v[148:151], v[208:211]
	v_mfma_f32_16x16x32_bf16 v[188:191], v[172:175], v[152:155], v[188:191]
	v_mfma_f32_16x16x32_bf16 v[192:195], v[164:167], v[152:155], v[192:195]
	v_mfma_f32_16x16x32_bf16 v[196:199], v[176:179], v[140:143], v[212:215]
	v_mfma_f32_16x16x32_bf16 v[200:203], v[168:171], v[140:143], v[242:245]
	v_mfma_f32_16x16x32_bf16 v[196:199], v[172:175], v[144:147], v[196:199]
	v_mfma_f32_16x16x32_bf16 v[200:203], v[164:167], v[144:147], v[200:203]
	s_nop 2
	v_exp_f32_e32 v188, v188
	v_exp_f32_e32 v189, v189
	v_exp_f32_e32 v190, v190
	v_exp_f32_e32 v191, v191
	v_exp_f32_e32 v192, v192
	v_exp_f32_e32 v193, v193
	v_exp_f32_e32 v194, v194
	v_exp_f32_e32 v195, v195
	v_cvt_pk_bf16_f32 v246, v188, v189
	v_cvt_pk_bf16_f32 v247, v190, v191
	v_cvt_pk_bf16_f32 v248, v192, v193
	v_cvt_pk_bf16_f32 v249, v194, v195
	v_add_f32_e32 v188, v188, v189
	v_add_f32_e32 v190, v190, v191
	v_add_f32_e32 v192, v192, v193
	v_add_f32_e32 v194, v194, v195
	v_add_f32_e32 v188, v188, v190
	v_add_f32_e32 v192, v192, v194
	v_add_f32_e32 v188, v188, v192
	v_add_f32_e32 v224, v224, v188
	v_mfma_f32_16x16x32_bf16 v[188:191], v[176:179], v[132:135], v[180:183]
	v_mfma_f32_16x16x32_bf16 v[192:195], v[168:171], v[132:135], v[184:187]
	v_mfma_f32_16x16x32_bf16 v[188:191], v[172:175], v[136:139], v[188:191]
	v_mfma_f32_16x16x32_bf16 v[192:195], v[164:167], v[136:139], v[192:195]
	v_exp_f32_e32 v196, v196
	v_exp_f32_e32 v197, v197
	v_exp_f32_e32 v198, v198
	v_exp_f32_e32 v199, v199
	v_mfma_f32_16x16x32_bf16 v[128:131], v[32:35], v[246:249], v[128:131]
	v_exp_f32_e32 v200, v200
	v_exp_f32_e32 v201, v201
	v_exp_f32_e32 v202, v202
	v_exp_f32_e32 v203, v203
	v_mfma_f32_16x16x32_bf16 v[124:127], v[28:31], v[246:249], v[124:127]
	v_cvt_pk_bf16_f32 v92, v196, v197
	v_cvt_pk_bf16_f32 v93, v198, v199
	v_cvt_pk_bf16_f32 v94, v200, v201
	v_cvt_pk_bf16_f32 v95, v202, v203
	v_mfma_f32_16x16x32_bf16 v[120:123], v[24:27], v[246:249], v[120:123]
	v_add_f32_e32 v196, v196, v197
	v_add_f32_e32 v198, v198, v199
	v_add_f32_e32 v200, v200, v201
	v_add_f32_e32 v202, v202, v203
	v_mfma_f32_16x16x32_bf16 v[116:119], v[20:23], v[246:249], v[116:119]
	v_add_f32_e32 v196, v196, v198
	v_add_f32_e32 v200, v200, v202
	v_add_f32_e32 v196, v196, v200
	v_add_f32_e32 v223, v223, v196
	v_exp_f32_e32 v188, v188
	v_exp_f32_e32 v189, v189
	v_exp_f32_e32 v190, v190
	v_exp_f32_e32 v191, v191
	v_mfma_f32_16x16x32_bf16 v[64:67], v[32:35], v[92:95], v[64:67]
	v_exp_f32_e32 v192, v192
	v_exp_f32_e32 v193, v193
	v_exp_f32_e32 v194, v194
	v_exp_f32_e32 v195, v195
	v_mfma_f32_16x16x32_bf16 v[60:63], v[28:31], v[92:95], v[60:63]
	v_cvt_pk_bf16_f32 v246, v188, v189
	v_cvt_pk_bf16_f32 v247, v190, v191
	v_cvt_pk_bf16_f32 v248, v192, v193
	v_cvt_pk_bf16_f32 v249, v194, v195
	v_mfma_f32_16x16x32_bf16 v[56:59], v[24:27], v[92:95], v[56:59]
	v_add_f32_e32 v188, v188, v189
	v_add_f32_e32 v190, v190, v191
	v_add_f32_e32 v192, v192, v193
	v_add_f32_e32 v194, v194, v195
	v_mfma_f32_16x16x32_bf16 v[52:55], v[20:23], v[92:95], v[52:55]
	v_add_f32_e32 v188, v188, v190
	v_add_f32_e32 v192, v192, v194
	v_add_f32_e32 v188, v188, v192
	v_add_f32_e32 v222, v222, v188
	s_waitcnt lgkmcnt(0)
	v_sub_f32_e32 v80, v80, v239
	v_sub_f32_e32 v81, v81, v239
	v_sub_f32_e32 v82, v82, v239
	v_mfma_f32_16x16x32_bf16 v[96:99], v[32:35], v[246:249], v[96:99]
	v_sub_f32_e32 v83, v83, v239
	v_sub_f32_e32 v84, v84, v239
	v_sub_f32_e32 v85, v85, v239
	v_mfma_f32_16x16x32_bf16 v[88:91], v[28:31], v[246:249], v[88:91]
	v_sub_f32_e32 v86, v86, v239
	v_sub_f32_e32 v87, v87, v239
	v_cndmask_b32_e64 v80, v238, v80, s[0:1]
	v_mfma_f32_16x16x32_bf16 v[72:75], v[24:27], v[246:249], v[72:75]
	v_cndmask_b32_e64 v81, v238, v81, s[6:7]
	v_cndmask_b32_e64 v82, v238, v82, s[8:9]
	v_cndmask_b32_e64 v83, v238, v83, s[10:11]
	v_mfma_f32_16x16x32_bf16 v[68:71], v[20:23], v[246:249], v[68:71]
	v_cndmask_b32_e64 v84, v238, v84, s[12:13]
	v_cndmask_b32_e64 v85, v238, v85, s[14:15]
	v_cndmask_b32_e64 v86, v238, v86, s[16:17]
	v_cndmask_b32_e64 v87, v238, v87, s[18:19]
	v_add_u32_e32 v240, 0x100, v240
	s_waitcnt lgkmcnt(0)
	ds_read_b128 v[176:179], v1 offset:0
	ds_read_b128 v[168:171], v1 offset:4096
	ds_read_b128 v[172:175], v1 offset:2048
	ds_read_b128 v[164:167], v1 offset:6144
	ds_read_b128 v[32:35], v221 offset:0
	ds_read_b128 v[28:31], v221 offset:2048
	ds_read_b128 v[24:27], v221 offset:4096
	ds_read_b128 v[20:23], v221 offset:6144
	v_mfma_f32_16x16x32_bf16 v[188:191], v[48:51], v[156:159], v[204:207]
	v_mfma_f32_16x16x32_bf16 v[192:195], v[40:43], v[156:159], v[208:211]
	v_mfma_f32_16x16x32_bf16 v[188:191], v[44:47], v[160:163], v[188:191]
	v_mfma_f32_16x16x32_bf16 v[192:195], v[36:39], v[160:163], v[192:195]
	ds_read2_b32 v[204:205], v240 offset0:0 offset1:1
	ds_read2_b32 v[206:207], v240 offset0:2 offset1:3
	ds_read2_b32 v[208:209], v240 offset0:4 offset1:5
	ds_read2_b32 v[210:211], v240 offset0:6 offset1:7
	v_mfma_f32_16x16x32_bf16 v[196:199], v[48:51], v[148:151], v[212:215]
	v_mfma_f32_16x16x32_bf16 v[200:203], v[40:43], v[148:151], v[242:245]
	v_mfma_f32_16x16x32_bf16 v[196:199], v[44:47], v[152:155], v[196:199]
	v_mfma_f32_16x16x32_bf16 v[200:203], v[36:39], v[152:155], v[200:203]
	v_exp_f32_e32 v188, v188
	v_exp_f32_e32 v189, v189
	v_exp_f32_e32 v190, v190
	v_exp_f32_e32 v191, v191
	v_exp_f32_e32 v192, v192
	v_exp_f32_e32 v193, v193
	v_exp_f32_e32 v194, v194
	v_exp_f32_e32 v195, v195
	v_cvt_pk_bf16_f32 v246, v188, v189
	v_cvt_pk_bf16_f32 v247, v190, v191
	v_cvt_pk_bf16_f32 v248, v192, v193
	v_cvt_pk_bf16_f32 v249, v194, v195
	v_add_f32_e32 v188, v188, v189
	v_add_f32_e32 v190, v190, v191
	v_add_f32_e32 v192, v192, v193
	v_add_f32_e32 v194, v194, v195
	v_add_f32_e32 v188, v188, v190
	v_add_f32_e32 v192, v192, v194
	v_add_f32_e32 v188, v188, v192
	v_add_f32_e32 v225, v225, v188
	v_mfma_f32_16x16x32_bf16 v[188:191], v[48:51], v[140:143], v[180:183]
	v_mfma_f32_16x16x32_bf16 v[192:195], v[40:43], v[140:143], v[184:187]
	v_mfma_f32_16x16x32_bf16 v[188:191], v[44:47], v[144:147], v[188:191]
	v_mfma_f32_16x16x32_bf16 v[192:195], v[36:39], v[144:147], v[192:195]
	v_exp_f32_e32 v196, v196
	v_exp_f32_e32 v197, v197
	v_exp_f32_e32 v198, v198
	v_exp_f32_e32 v199, v199
	v_mfma_f32_16x16x32_bf16 v[112:115], v[16:19], v[246:249], v[112:115]
	v_exp_f32_e32 v200, v200
	v_exp_f32_e32 v201, v201
	v_exp_f32_e32 v202, v202
	v_exp_f32_e32 v203, v203
	v_mfma_f32_16x16x32_bf16 v[108:111], v[12:15], v[246:249], v[108:111]
	v_cvt_pk_bf16_f32 v92, v196, v197
	v_cvt_pk_bf16_f32 v93, v198, v199
	v_cvt_pk_bf16_f32 v94, v200, v201
	v_cvt_pk_bf16_f32 v95, v202, v203
	v_mfma_f32_16x16x32_bf16 v[104:107], v[8:11], v[246:249], v[104:107]
	v_add_f32_e32 v196, v196, v197
	v_add_f32_e32 v198, v198, v199
	v_add_f32_e32 v200, v200, v201
	v_add_f32_e32 v202, v202, v203
	v_mfma_f32_16x16x32_bf16 v[100:103], v[4:7], v[246:249], v[100:103]
	v_add_f32_e32 v196, v196, v198
	v_add_f32_e32 v200, v200, v202
	v_add_f32_e32 v196, v196, v200
	v_add_f32_e32 v224, v224, v196
	v_mfma_f32_16x16x32_bf16 v[196:199], v[48:51], v[132:135], v[80:83]
	v_mfma_f32_16x16x32_bf16 v[200:203], v[40:43], v[132:135], v[84:87]
	v_mfma_f32_16x16x32_bf16 v[196:199], v[44:47], v[136:139], v[196:199]
	v_mfma_f32_16x16x32_bf16 v[200:203], v[36:39], v[136:139], v[200:203]
	v_exp_f32_e32 v188, v188
	v_exp_f32_e32 v189, v189
	v_exp_f32_e32 v190, v190
	v_exp_f32_e32 v191, v191
	v_mfma_f32_16x16x32_bf16 v[128:131], v[16:19], v[92:95], v[128:131]
	v_exp_f32_e32 v192, v192
	v_exp_f32_e32 v193, v193
	v_exp_f32_e32 v194, v194
	v_exp_f32_e32 v195, v195
	v_mfma_f32_16x16x32_bf16 v[124:127], v[12:15], v[92:95], v[124:127]
	v_cvt_pk_bf16_f32 v246, v188, v189
	v_cvt_pk_bf16_f32 v247, v190, v191
	v_cvt_pk_bf16_f32 v248, v192, v193
	v_cvt_pk_bf16_f32 v249, v194, v195
	v_mfma_f32_16x16x32_bf16 v[120:123], v[8:11], v[92:95], v[120:123]
	v_add_f32_e32 v188, v188, v189
	v_add_f32_e32 v190, v190, v191
	v_add_f32_e32 v192, v192, v193
	v_add_f32_e32 v194, v194, v195
	v_mfma_f32_16x16x32_bf16 v[116:119], v[4:7], v[92:95], v[116:119]
	v_add_f32_e32 v188, v188, v190
	v_add_f32_e32 v192, v192, v194
	v_add_f32_e32 v188, v188, v192
	v_add_f32_e32 v223, v223, v188
	v_exp_f32_e32 v196, v196
	v_exp_f32_e32 v197, v197
	v_exp_f32_e32 v198, v198
	v_exp_f32_e32 v199, v199
	v_mfma_f32_16x16x32_bf16 v[64:67], v[16:19], v[246:249], v[64:67]
	v_exp_f32_e32 v200, v200
	v_exp_f32_e32 v201, v201
	v_exp_f32_e32 v202, v202
	v_exp_f32_e32 v203, v203
	v_mfma_f32_16x16x32_bf16 v[60:63], v[12:15], v[246:249], v[60:63]
	v_cvt_pk_bf16_f32 v92, v196, v197
	v_cvt_pk_bf16_f32 v93, v198, v199
	v_cvt_pk_bf16_f32 v94, v200, v201
	v_cvt_pk_bf16_f32 v95, v202, v203
	v_mfma_f32_16x16x32_bf16 v[56:59], v[8:11], v[246:249], v[56:59]
	v_add_f32_e32 v196, v196, v197
	v_add_f32_e32 v198, v198, v199
	v_add_f32_e32 v200, v200, v201
	v_add_f32_e32 v202, v202, v203
	v_mfma_f32_16x16x32_bf16 v[52:55], v[4:7], v[246:249], v[52:55]
	v_add_f32_e32 v196, v196, v198
	v_add_f32_e32 v200, v200, v202
	v_add_f32_e32 v196, v196, v200
	v_add_f32_e32 v222, v222, v196
	s_waitcnt lgkmcnt(0)
	v_sub_f32_e32 v204, v204, v239
	v_sub_f32_e32 v205, v205, v239
	v_sub_f32_e32 v206, v206, v239
	v_mfma_f32_16x16x32_bf16 v[96:99], v[16:19], v[92:95], v[96:99]
	v_sub_f32_e32 v207, v207, v239
	v_sub_f32_e32 v208, v208, v239
	v_sub_f32_e32 v209, v209, v239
	v_mfma_f32_16x16x32_bf16 v[88:91], v[12:15], v[92:95], v[88:91]
	v_sub_f32_e32 v210, v210, v239
	v_sub_f32_e32 v211, v211, v239
	v_cndmask_b32_e64 v204, v238, v204, s[0:1]
	v_mfma_f32_16x16x32_bf16 v[72:75], v[8:11], v[92:95], v[72:75]
	v_cndmask_b32_e64 v205, v238, v205, s[6:7]
	v_cndmask_b32_e64 v206, v238, v206, s[8:9]
	v_cndmask_b32_e64 v207, v238, v207, s[10:11]
	v_mfma_f32_16x16x32_bf16 v[68:71], v[4:7], v[92:95], v[68:71]
	v_cndmask_b32_e64 v208, v238, v208, s[12:13]
	v_cndmask_b32_e64 v209, v238, v209, s[14:15]
	v_cndmask_b32_e64 v210, v238, v210, s[16:17]
	v_cndmask_b32_e64 v211, v238, v211, s[18:19]
	v_add_u32_e32 v240, 0x100, v240
	s_waitcnt lgkmcnt(0)
	s_waitcnt vmcnt(0)
	s_cmp_gt_i32 s63, -2
	s_cbranch_scc0 .Latt_eb9
	s_barrier

.Latt_dk10:
	s_add_u32 s95, s95, 0x20000
	s_add_u32 s92, s92, 0x100
	s_sub_i32 s63, s63, 2
	ds_read_b128 v[48:51], v2 offset:0
	ds_read_b128 v[40:43], v2 offset:4096
	ds_read_b128 v[44:47], v2 offset:2048
	ds_read_b128 v[36:39], v2 offset:6144
	ds_read_b128 v[16:19], v235 offset:0
	ds_read_b128 v[12:15], v235 offset:2048
	ds_read_b128 v[8:11], v235 offset:4096
	ds_read_b128 v[4:7], v235 offset:6144
	v_mfma_f32_16x16x32_bf16 v[188:191], v[176:179], v[156:159], v[212:215]
	v_mfma_f32_16x16x32_bf16 v[192:195], v[168:171], v[156:159], v[242:245]
	v_mfma_f32_16x16x32_bf16 v[188:191], v[172:175], v[160:163], v[188:191]
	v_mfma_f32_16x16x32_bf16 v[192:195], v[164:167], v[160:163], v[192:195]
	ds_read2_b32 v[212:213], v240 offset0:0 offset1:1
	ds_read2_b32 v[214:215], v240 offset0:2 offset1:3
	ds_read2_b32 v[242:243], v240 offset0:4 offset1:5
	ds_read2_b32 v[244:245], v240 offset0:6 offset1:7
	v_mfma_f32_16x16x32_bf16 v[196:199], v[176:179], v[148:151], v[180:183]
	v_mfma_f32_16x16x32_bf16 v[200:203], v[168:171], v[148:151], v[184:187]
	v_mfma_f32_16x16x32_bf16 v[196:199], v[172:175], v[152:155], v[196:199]
	v_mfma_f32_16x16x32_bf16 v[200:203], v[164:167], v[152:155], v[200:203]
	v_exp_f32_e32 v188, v188
	v_exp_f32_e32 v189, v189
	v_exp_f32_e32 v190, v190
	v_exp_f32_e32 v191, v191
	v_exp_f32_e32 v192, v192
	v_exp_f32_e32 v193, v193
	v_exp_f32_e32 v194, v194
	v_exp_f32_e32 v195, v195
	v_cvt_pk_bf16_f32 v246, v188, v189
	v_cvt_pk_bf16_f32 v247, v190, v191
	v_cvt_pk_bf16_f32 v248, v192, v193
	v_cvt_pk_bf16_f32 v249, v194, v195
	v_add_f32_e32 v188, v188, v189
	v_add_f32_e32 v190, v190, v191
	v_add_f32_e32 v192, v192, v193
	v_add_f32_e32 v194, v194, v195
	v_add_f32_e32 v188, v188, v190
	v_add_f32_e32 v192, v192, v194
	v_add_f32_e32 v188, v188, v192
	v_add_f32_e32 v225, v225, v188
	v_mfma_f32_16x16x32_bf16 v[188:191], v[176:179], v[140:143], v[80:83]
	v_mfma_f32_16x16x32_bf16 v[192:195], v[168:171], v[140:143], v[84:87]
	v_mfma_f32_16x16x32_bf16 v[188:191], v[172:175], v[144:147], v[188:191]
	v_mfma_f32_16x16x32_bf16 v[192:195], v[164:167], v[144:147], v[192:195]
	v_exp_f32_e32 v196, v196
	v_exp_f32_e32 v197, v197
	v_exp_f32_e32 v198, v198
	v_exp_f32_e32 v199, v199
	v_mfma_f32_16x16x32_bf16 v[112:115], v[32:35], v[246:249], v[112:115]
	v_exp_f32_e32 v200, v200
	v_exp_f32_e32 v201, v201
	v_exp_f32_e32 v202, v202
	v_exp_f32_e32 v203, v203
	v_mfma_f32_16x16x32_bf16 v[108:111], v[28:31], v[246:249], v[108:111]
	v_cvt_pk_bf16_f32 v92, v196, v197
	v_cvt_pk_bf16_f32 v93, v198, v199
	v_cvt_pk_bf16_f32 v94, v200, v201
	v_cvt_pk_bf16_f32 v95, v202, v203
	v_mfma_f32_16x16x32_bf16 v[104:107], v[24:27], v[246:249], v[104:107]
	v_add_f32_e32 v196, v196, v197
	v_add_f32_e32 v198, v198, v199
	v_add_f32_e32 v200, v200, v201
	v_add_f32_e32 v202, v202, v203
	v_mfma_f32_16x16x32_bf16 v[100:103], v[20:23], v[246:249], v[100:103]
	v_add_f32_e32 v196, v196, v198
	v_add_f32_e32 v200, v200, v202
	v_add_f32_e32 v196, v196, v200
	v_add_f32_e32 v224, v224, v196
	v_mfma_f32_16x16x32_bf16 v[196:199], v[176:179], v[132:135], v[204:207]
	v_mfma_f32_16x16x32_bf16 v[200:203], v[168:171], v[132:135], v[208:211]
	v_mfma_f32_16x16x32_bf16 v[196:199], v[172:175], v[136:139], v[196:199]
	v_mfma_f32_16x16x32_bf16 v[200:203], v[164:167], v[136:139], v[200:203]
	v_exp_f32_e32 v188, v188
	v_exp_f32_e32 v189, v189
	v_exp_f32_e32 v190, v190
	v_exp_f32_e32 v191, v191
	v_mfma_f32_16x16x32_bf16 v[128:131], v[32:35], v[92:95], v[128:131]
	v_exp_f32_e32 v192, v192
	v_exp_f32_e32 v193, v193
	v_exp_f32_e32 v194, v194
	v_exp_f32_e32 v195, v195
	v_mfma_f32_16x16x32_bf16 v[124:127], v[28:31], v[92:95], v[124:127]
	v_cvt_pk_bf16_f32 v246, v188, v189
	v_cvt_pk_bf16_f32 v247, v190, v191
	v_cvt_pk_bf16_f32 v248, v192, v193
	v_cvt_pk_bf16_f32 v249, v194, v195
	v_mfma_f32_16x16x32_bf16 v[120:123], v[24:27], v[92:95], v[120:123]
	v_add_f32_e32 v188, v188, v189
	v_add_f32_e32 v190, v190, v191
	v_add_f32_e32 v192, v192, v193
	v_add_f32_e32 v194, v194, v195
	v_mfma_f32_16x16x32_bf16 v[116:119], v[20:23], v[92:95], v[116:119]
	v_add_f32_e32 v188, v188, v190
	v_add_f32_e32 v192, v192, v194
	v_add_f32_e32 v188, v188, v192
	v_add_f32_e32 v223, v223, v188
	v_exp_f32_e32 v196, v196
	v_exp_f32_e32 v197, v197
	v_exp_f32_e32 v198, v198
	v_exp_f32_e32 v199, v199
	v_mfma_f32_16x16x32_bf16 v[64:67], v[32:35], v[246:249], v[64:67]
	v_exp_f32_e32 v200, v200
	v_exp_f32_e32 v201, v201
	v_exp_f32_e32 v202, v202
	v_exp_f32_e32 v203, v203
	v_mfma_f32_16x16x32_bf16 v[60:63], v[28:31], v[246:249], v[60:63]
	v_cvt_pk_bf16_f32 v92, v196, v197
	v_cvt_pk_bf16_f32 v93, v198, v199
	v_cvt_pk_bf16_f32 v94, v200, v201
	v_cvt_pk_bf16_f32 v95, v202, v203
	v_mfma_f32_16x16x32_bf16 v[56:59], v[24:27], v[246:249], v[56:59]
	v_add_f32_e32 v196, v196, v197
	v_add_f32_e32 v198, v198, v199
	v_add_f32_e32 v200, v200, v201
	v_add_f32_e32 v202, v202, v203
	v_mfma_f32_16x16x32_bf16 v[52:55], v[20:23], v[246:249], v[52:55]
	v_add_f32_e32 v196, v196, v198
	v_add_f32_e32 v200, v200, v202
	v_add_f32_e32 v196, v196, v200
	v_add_f32_e32 v222, v222, v196
	s_waitcnt lgkmcnt(0)
	v_sub_f32_e32 v212, v212, v239
	v_sub_f32_e32 v213, v213, v239
	v_sub_f32_e32 v214, v214, v239
	v_mfma_f32_16x16x32_bf16 v[96:99], v[32:35], v[92:95], v[96:99]
	v_sub_f32_e32 v215, v215, v239
	v_sub_f32_e32 v242, v242, v239
	v_sub_f32_e32 v243, v243, v239
	v_mfma_f32_16x16x32_bf16 v[88:91], v[28:31], v[92:95], v[88:91]
	v_sub_f32_e32 v244, v244, v239
	v_sub_f32_e32 v245, v245, v239
	v_cndmask_b32_e64 v212, v238, v212, s[0:1]
	v_mfma_f32_16x16x32_bf16 v[72:75], v[24:27], v[92:95], v[72:75]
	v_cndmask_b32_e64 v213, v238, v213, s[6:7]
	v_cndmask_b32_e64 v214, v238, v214, s[8:9]
	v_cndmask_b32_e64 v215, v238, v215, s[10:11]
	v_mfma_f32_16x16x32_bf16 v[68:71], v[20:23], v[92:95], v[68:71]
	v_cndmask_b32_e64 v242, v238, v242, s[12:13]
	v_cndmask_b32_e64 v243, v238, v243, s[14:15]
	v_cndmask_b32_e64 v244, v238, v244, s[16:17]
	v_cndmask_b32_e64 v245, v238, v245, s[18:19]
	v_add_u32_e32 v240, 0x100, v240
	s_waitcnt lgkmcnt(0)
	ds_read_b128 v[176:179], v3 offset:0
	ds_read_b128 v[168:171], v3 offset:4096
	ds_read_b128 v[172:175], v3 offset:2048
	ds_read_b128 v[164:167], v3 offset:6144
	ds_read_b128 v[32:35], v250 offset:0
	ds_read_b128 v[28:31], v250 offset:2048
	ds_read_b128 v[24:27], v250 offset:4096
	ds_read_b128 v[20:23], v250 offset:6144
	v_mfma_f32_16x16x32_bf16 v[188:191], v[48:51], v[156:159], v[180:183]
	v_mfma_f32_16x16x32_bf16 v[192:195], v[40:43], v[156:159], v[184:187]
	v_mfma_f32_16x16x32_bf16 v[188:191], v[44:47], v[160:163], v[188:191]
	v_mfma_f32_16x16x32_bf16 v[192:195], v[36:39], v[160:163], v[192:195]
	ds_read2_b32 v[180:181], v240 offset0:0 offset1:1
	ds_read2_b32 v[182:183], v240 offset0:2 offset1:3
	ds_read2_b32 v[184:185], v240 offset0:4 offset1:5
	ds_read2_b32 v[186:187], v240 offset0:6 offset1:7
	v_mfma_f32_16x16x32_bf16 v[196:199], v[48:51], v[148:151], v[80:83]
	v_mfma_f32_16x16x32_bf16 v[200:203], v[40:43], v[148:151], v[84:87]
	v_mfma_f32_16x16x32_bf16 v[196:199], v[44:47], v[152:155], v[196:199]
	v_mfma_f32_16x16x32_bf16 v[200:203], v[36:39], v[152:155], v[200:203]
	v_exp_f32_e32 v188, v188
	v_exp_f32_e32 v189, v189
	v_exp_f32_e32 v190, v190
	v_exp_f32_e32 v191, v191
	v_exp_f32_e32 v192, v192
	v_exp_f32_e32 v193, v193
	v_exp_f32_e32 v194, v194
	v_exp_f32_e32 v195, v195
	v_cvt_pk_bf16_f32 v246, v188, v189
	v_cvt_pk_bf16_f32 v247, v190, v191
	v_cvt_pk_bf16_f32 v248, v192, v193
	v_cvt_pk_bf16_f32 v249, v194, v195
	v_add_f32_e32 v188, v188, v189
	v_add_f32_e32 v190, v190, v191
	v_add_f32_e32 v192, v192, v193
	v_add_f32_e32 v194, v194, v195
	v_add_f32_e32 v188, v188, v190
	v_add_f32_e32 v192, v192, v194
	v_add_f32_e32 v188, v188, v192
	v_add_f32_e32 v225, v225, v188
	v_mfma_f32_16x16x32_bf16 v[188:191], v[48:51], v[140:143], v[204:207]
	v_mfma_f32_16x16x32_bf16 v[192:195], v[40:43], v[140:143], v[208:211]
	v_mfma_f32_16x16x32_bf16 v[188:191], v[44:47], v[144:147], v[188:191]
	v_mfma_f32_16x16x32_bf16 v[192:195], v[36:39], v[144:147], v[192:195]
	v_exp_f32_e32 v196, v196
	v_exp_f32_e32 v197, v197
	v_exp_f32_e32 v198, v198
	v_exp_f32_e32 v199, v199
	v_mfma_f32_16x16x32_bf16 v[112:115], v[16:19], v[246:249], v[112:115]
	v_exp_f32_e32 v200, v200
	v_exp_f32_e32 v201, v201
	v_exp_f32_e32 v202, v202
	v_exp_f32_e32 v203, v203
	v_mfma_f32_16x16x32_bf16 v[108:111], v[12:15], v[246:249], v[108:111]
	v_cvt_pk_bf16_f32 v92, v196, v197
	v_cvt_pk_bf16_f32 v93, v198, v199
	v_cvt_pk_bf16_f32 v94, v200, v201
	v_cvt_pk_bf16_f32 v95, v202, v203
	v_mfma_f32_16x16x32_bf16 v[104:107], v[8:11], v[246:249], v[104:107]
	v_add_f32_e32 v196, v196, v197
	v_add_f32_e32 v198, v198, v199
	v_add_f32_e32 v200, v200, v201
	v_add_f32_e32 v202, v202, v203
	v_mfma_f32_16x16x32_bf16 v[100:103], v[4:7], v[246:249], v[100:103]
	v_add_f32_e32 v196, v196, v198
	v_add_f32_e32 v200, v200, v202
	v_add_f32_e32 v196, v196, v200
	v_add_f32_e32 v224, v224, v196
	v_mfma_f32_16x16x32_bf16 v[196:199], v[48:51], v[132:135], v[212:215]
	v_mfma_f32_16x16x32_bf16 v[200:203], v[40:43], v[132:135], v[242:245]
	v_mfma_f32_16x16x32_bf16 v[196:199], v[44:47], v[136:139], v[196:199]
	v_mfma_f32_16x16x32_bf16 v[200:203], v[36:39], v[136:139], v[200:203]
	v_exp_f32_e32 v188, v188
	v_exp_f32_e32 v189, v189
	v_exp_f32_e32 v190, v190
	v_exp_f32_e32 v191, v191
	v_mfma_f32_16x16x32_bf16 v[128:131], v[16:19], v[92:95], v[128:131]
	v_exp_f32_e32 v192, v192
	v_exp_f32_e32 v193, v193
	v_exp_f32_e32 v194, v194
	v_exp_f32_e32 v195, v195
	v_mfma_f32_16x16x32_bf16 v[124:127], v[12:15], v[92:95], v[124:127]
	v_cvt_pk_bf16_f32 v246, v188, v189
	v_cvt_pk_bf16_f32 v247, v190, v191
	v_cvt_pk_bf16_f32 v248, v192, v193
	v_cvt_pk_bf16_f32 v249, v194, v195
	v_mfma_f32_16x16x32_bf16 v[120:123], v[8:11], v[92:95], v[120:123]
	v_add_f32_e32 v188, v188, v189
	v_add_f32_e32 v190, v190, v191
	v_add_f32_e32 v192, v192, v193
	v_add_f32_e32 v194, v194, v195
	v_mfma_f32_16x16x32_bf16 v[116:119], v[4:7], v[92:95], v[116:119]
	v_add_f32_e32 v188, v188, v190
	v_add_f32_e32 v192, v192, v194
	v_add_f32_e32 v188, v188, v192
	v_add_f32_e32 v223, v223, v188
	v_exp_f32_e32 v196, v196
	v_exp_f32_e32 v197, v197
	v_exp_f32_e32 v198, v198
	v_exp_f32_e32 v199, v199
	v_mfma_f32_16x16x32_bf16 v[64:67], v[16:19], v[246:249], v[64:67]
	v_exp_f32_e32 v200, v200
	v_exp_f32_e32 v201, v201
	v_exp_f32_e32 v202, v202
	v_exp_f32_e32 v203, v203
	v_mfma_f32_16x16x32_bf16 v[60:63], v[12:15], v[246:249], v[60:63]
	v_cvt_pk_bf16_f32 v92, v196, v197
	v_cvt_pk_bf16_f32 v93, v198, v199
	v_cvt_pk_bf16_f32 v94, v200, v201
	v_cvt_pk_bf16_f32 v95, v202, v203
	v_mfma_f32_16x16x32_bf16 v[56:59], v[8:11], v[246:249], v[56:59]
	v_add_f32_e32 v196, v196, v197
	v_add_f32_e32 v198, v198, v199
	v_add_f32_e32 v200, v200, v201
	v_add_f32_e32 v202, v202, v203
	v_mfma_f32_16x16x32_bf16 v[52:55], v[4:7], v[246:249], v[52:55]
	v_add_f32_e32 v196, v196, v198
	v_add_f32_e32 v200, v200, v202
	v_add_f32_e32 v196, v196, v200
	v_add_f32_e32 v222, v222, v196
	s_waitcnt lgkmcnt(0)
	v_sub_f32_e32 v180, v180, v239
	v_sub_f32_e32 v181, v181, v239
	v_sub_f32_e32 v182, v182, v239
	v_mfma_f32_16x16x32_bf16 v[96:99], v[16:19], v[92:95], v[96:99]
	v_sub_f32_e32 v183, v183, v239
	v_sub_f32_e32 v184, v184, v239
	v_sub_f32_e32 v185, v185, v239
	v_mfma_f32_16x16x32_bf16 v[88:91], v[12:15], v[92:95], v[88:91]
	v_sub_f32_e32 v186, v186, v239
	v_sub_f32_e32 v187, v187, v239
	v_cndmask_b32_e64 v180, v238, v180, s[0:1]
	v_mfma_f32_16x16x32_bf16 v[72:75], v[8:11], v[92:95], v[72:75]
	v_cndmask_b32_e64 v181, v238, v181, s[6:7]
	v_cndmask_b32_e64 v182, v238, v182, s[8:9]
	v_cndmask_b32_e64 v183, v238, v183, s[10:11]
	v_mfma_f32_16x16x32_bf16 v[68:71], v[4:7], v[92:95], v[68:71]
	v_cndmask_b32_e64 v184, v238, v184, s[12:13]
	v_cndmask_b32_e64 v185, v238, v185, s[14:15]
	v_cndmask_b32_e64 v186, v238, v186, s[16:17]
	v_cndmask_b32_e64 v187, v238, v187, s[18:19]
	v_add_u32_e32 v240, 0x100, v240
	s_waitcnt lgkmcnt(0)
	s_waitcnt vmcnt(0)
	s_cmp_gt_i32 s63, -2
	s_cbranch_scc0 .Latt_eb11
	s_barrier

.Latt_dk12:
	s_add_u32 s95, s95, 0x20000
	s_add_u32 s92, s92, 0x100
	s_sub_i32 s63, s63, 2
	ds_read_b128 v[48:51], v220 offset:0
	ds_read_b128 v[40:43], v220 offset:4096
	ds_read_b128 v[44:47], v220 offset:2048
	ds_read_b128 v[36:39], v220 offset:6144
	ds_read_b128 v[16:19], v254 offset:0
	ds_read_b128 v[12:15], v254 offset:2048
	ds_read_b128 v[8:11], v254 offset:4096
	ds_read_b128 v[4:7], v254 offset:6144
	v_mfma_f32_16x16x32_bf16 v[188:191], v[176:179], v[156:159], v[80:83]
	v_mfma_f32_16x16x32_bf16 v[192:195], v[168:171], v[156:159], v[84:87]
	v_mfma_f32_16x16x32_bf16 v[188:191], v[172:175], v[160:163], v[188:191]
	v_mfma_f32_16x16x32_bf16 v[192:195], v[164:167], v[160:163], v[192:195]
	ds_read2_b32 v[80:81], v240 offset0:0 offset1:1
	ds_read2_b32 v[82:83], v240 offset0:2 offset1:3
	ds_read2_b32 v[84:85], v240 offset0:4 offset1:5
	ds_read2_b32 v[86:87], v240 offset0:6 offset1:7
	v_mfma_f32_16x16x32_bf16 v[196:199], v[176:179], v[148:151], v[204:207]
	v_mfma_f32_16x16x32_bf16 v[200:203], v[168:171], v[148:151], v[208:211]
	v_mfma_f32_16x16x32_bf16 v[196:199], v[172:175], v[152:155], v[196:199]
	v_mfma_f32_16x16x32_bf16 v[200:203], v[164:167], v[152:155], v[200:203]
	v_exp_f32_e32 v188, v188
	v_exp_f32_e32 v189, v189
	v_exp_f32_e32 v190, v190
	v_exp_f32_e32 v191, v191
	v_exp_f32_e32 v192, v192
	v_exp_f32_e32 v193, v193
	v_exp_f32_e32 v194, v194
	v_exp_f32_e32 v195, v195
	v_cvt_pk_bf16_f32 v246, v188, v189
	v_cvt_pk_bf16_f32 v247, v190, v191
	v_cvt_pk_bf16_f32 v248, v192, v193
	v_cvt_pk_bf16_f32 v249, v194, v195
	v_add_f32_e32 v188, v188, v189
	v_add_f32_e32 v190, v190, v191
	v_add_f32_e32 v192, v192, v193
	v_add_f32_e32 v194, v194, v195
	v_add_f32_e32 v188, v188, v190
	v_add_f32_e32 v192, v192, v194
	v_add_f32_e32 v188, v188, v192
	v_add_f32_e32 v225, v225, v188
	v_mfma_f32_16x16x32_bf16 v[188:191], v[176:179], v[140:143], v[212:215]
	v_mfma_f32_16x16x32_bf16 v[192:195], v[168:171], v[140:143], v[242:245]
	v_mfma_f32_16x16x32_bf16 v[188:191], v[172:175], v[144:147], v[188:191]
	v_mfma_f32_16x16x32_bf16 v[192:195], v[164:167], v[144:147], v[192:195]
	v_exp_f32_e32 v196, v196
	v_exp_f32_e32 v197, v197
	v_exp_f32_e32 v198, v198
	v_exp_f32_e32 v199, v199
	v_mfma_f32_16x16x32_bf16 v[112:115], v[32:35], v[246:249], v[112:115]
	v_exp_f32_e32 v200, v200
	v_exp_f32_e32 v201, v201
	v_exp_f32_e32 v202, v202
	v_exp_f32_e32 v203, v203
	v_mfma_f32_16x16x32_bf16 v[108:111], v[28:31], v[246:249], v[108:111]
	v_cvt_pk_bf16_f32 v92, v196, v197
	v_cvt_pk_bf16_f32 v93, v198, v199
	v_cvt_pk_bf16_f32 v94, v200, v201
	v_cvt_pk_bf16_f32 v95, v202, v203
	v_mfma_f32_16x16x32_bf16 v[104:107], v[24:27], v[246:249], v[104:107]
	v_add_f32_e32 v196, v196, v197
	v_add_f32_e32 v198, v198, v199
	v_add_f32_e32 v200, v200, v201
	v_add_f32_e32 v202, v202, v203
	v_mfma_f32_16x16x32_bf16 v[100:103], v[20:23], v[246:249], v[100:103]
	v_add_f32_e32 v196, v196, v198
	v_add_f32_e32 v200, v200, v202
	v_add_f32_e32 v196, v196, v200
	v_add_f32_e32 v224, v224, v196
	v_mfma_f32_16x16x32_bf16 v[196:199], v[176:179], v[132:135], v[180:183]
	v_mfma_f32_16x16x32_bf16 v[200:203], v[168:171], v[132:135], v[184:187]
	v_mfma_f32_16x16x32_bf16 v[196:199], v[172:175], v[136:139], v[196:199]
	v_mfma_f32_16x16x32_bf16 v[200:203], v[164:167], v[136:139], v[200:203]
	v_exp_f32_e32 v188, v188
	v_exp_f32_e32 v189, v189
	v_exp_f32_e32 v190, v190
	v_exp_f32_e32 v191, v191
	v_mfma_f32_16x16x32_bf16 v[128:131], v[32:35], v[92:95], v[128:131]
	v_exp_f32_e32 v192, v192
	v_exp_f32_e32 v193, v193
	v_exp_f32_e32 v194, v194
	v_exp_f32_e32 v195, v195
	v_mfma_f32_16x16x32_bf16 v[124:127], v[28:31], v[92:95], v[124:127]
	v_cvt_pk_bf16_f32 v246, v188, v189
	v_cvt_pk_bf16_f32 v247, v190, v191
	v_cvt_pk_bf16_f32 v248, v192, v193
	v_cvt_pk_bf16_f32 v249, v194, v195
	v_mfma_f32_16x16x32_bf16 v[120:123], v[24:27], v[92:95], v[120:123]
	v_add_f32_e32 v188, v188, v189
	v_add_f32_e32 v190, v190, v191
	v_add_f32_e32 v192, v192, v193
	v_add_f32_e32 v194, v194, v195
	v_mfma_f32_16x16x32_bf16 v[116:119], v[20:23], v[92:95], v[116:119]
	v_add_f32_e32 v188, v188, v190
	v_add_f32_e32 v192, v192, v194
	v_add_f32_e32 v188, v188, v192
	v_add_f32_e32 v223, v223, v188
	v_exp_f32_e32 v196, v196
	v_exp_f32_e32 v197, v197
	v_exp_f32_e32 v198, v198
	v_exp_f32_e32 v199, v199
	v_mfma_f32_16x16x32_bf16 v[64:67], v[32:35], v[246:249], v[64:67]
	v_exp_f32_e32 v200, v200
	v_exp_f32_e32 v201, v201
	v_exp_f32_e32 v202, v202
	v_exp_f32_e32 v203, v203
	v_mfma_f32_16x16x32_bf16 v[60:63], v[28:31], v[246:249], v[60:63]
	v_cvt_pk_bf16_f32 v92, v196, v197
	v_cvt_pk_bf16_f32 v93, v198, v199
	v_cvt_pk_bf16_f32 v94, v200, v201
	v_cvt_pk_bf16_f32 v95, v202, v203
	v_mfma_f32_16x16x32_bf16 v[56:59], v[24:27], v[246:249], v[56:59]
	v_add_f32_e32 v196, v196, v197
	v_add_f32_e32 v198, v198, v199
	v_add_f32_e32 v200, v200, v201
	v_add_f32_e32 v202, v202, v203
	v_mfma_f32_16x16x32_bf16 v[52:55], v[20:23], v[246:249], v[52:55]
	v_add_f32_e32 v196, v196, v198
	v_add_f32_e32 v200, v200, v202
	v_add_f32_e32 v196, v196, v200
	v_add_f32_e32 v222, v222, v196
	s_waitcnt lgkmcnt(0)
	v_sub_f32_e32 v80, v80, v239
	v_sub_f32_e32 v81, v81, v239
	v_sub_f32_e32 v82, v82, v239
	v_mfma_f32_16x16x32_bf16 v[96:99], v[32:35], v[92:95], v[96:99]
	v_sub_f32_e32 v83, v83, v239
	v_sub_f32_e32 v84, v84, v239
	v_sub_f32_e32 v85, v85, v239
	v_mfma_f32_16x16x32_bf16 v[88:91], v[28:31], v[92:95], v[88:91]
	v_sub_f32_e32 v86, v86, v239
	v_sub_f32_e32 v87, v87, v239
	v_cndmask_b32_e64 v80, v238, v80, s[0:1]
	v_mfma_f32_16x16x32_bf16 v[72:75], v[24:27], v[92:95], v[72:75]
	v_cndmask_b32_e64 v81, v238, v81, s[6:7]
	v_cndmask_b32_e64 v82, v238, v82, s[8:9]
	v_cndmask_b32_e64 v83, v238, v83, s[10:11]
	v_mfma_f32_16x16x32_bf16 v[68:71], v[20:23], v[92:95], v[68:71]
	v_cndmask_b32_e64 v84, v238, v84, s[12:13]
	v_cndmask_b32_e64 v85, v238, v85, s[14:15]
	v_cndmask_b32_e64 v86, v238, v86, s[16:17]
	v_cndmask_b32_e64 v87, v238, v87, s[18:19]
	v_add_u32_e32 v240, 0x100, v240
	s_waitcnt lgkmcnt(0)
	ds_read_b128 v[176:179], v1 offset:0
	ds_read_b128 v[168:171], v1 offset:4096
	ds_read_b128 v[172:175], v1 offset:2048
	ds_read_b128 v[164:167], v1 offset:6144
	ds_read_b128 v[32:35], v221 offset:0
	ds_read_b128 v[28:31], v221 offset:2048
	ds_read_b128 v[24:27], v221 offset:4096
	ds_read_b128 v[20:23], v221 offset:6144
	v_mfma_f32_16x16x32_bf16 v[188:191], v[48:51], v[156:159], v[204:207]
	v_mfma_f32_16x16x32_bf16 v[192:195], v[40:43], v[156:159], v[208:211]
	v_mfma_f32_16x16x32_bf16 v[188:191], v[44:47], v[160:163], v[188:191]
	v_mfma_f32_16x16x32_bf16 v[192:195], v[36:39], v[160:163], v[192:195]
	v_mfma_f32_16x16x32_bf16 v[196:199], v[48:51], v[148:151], v[212:215]
	v_mfma_f32_16x16x32_bf16 v[200:203], v[40:43], v[148:151], v[242:245]
	v_mfma_f32_16x16x32_bf16 v[196:199], v[44:47], v[152:155], v[196:199]
	v_mfma_f32_16x16x32_bf16 v[200:203], v[36:39], v[152:155], v[200:203]
	s_nop 2
	v_exp_f32_e32 v188, v188
	v_exp_f32_e32 v189, v189
	v_exp_f32_e32 v190, v190
	v_exp_f32_e32 v191, v191
	v_exp_f32_e32 v192, v192
	v_exp_f32_e32 v193, v193
	v_exp_f32_e32 v194, v194
	v_exp_f32_e32 v195, v195
	v_cvt_pk_bf16_f32 v246, v188, v189
	v_cvt_pk_bf16_f32 v247, v190, v191
	v_cvt_pk_bf16_f32 v248, v192, v193
	v_cvt_pk_bf16_f32 v249, v194, v195
	v_add_f32_e32 v188, v188, v189
	v_add_f32_e32 v190, v190, v191
	v_add_f32_e32 v192, v192, v193
	v_add_f32_e32 v194, v194, v195
	v_add_f32_e32 v188, v188, v190
	v_add_f32_e32 v192, v192, v194
	v_add_f32_e32 v188, v188, v192
	v_add_f32_e32 v225, v225, v188
	v_mfma_f32_16x16x32_bf16 v[188:191], v[48:51], v[140:143], v[180:183]
	v_mfma_f32_16x16x32_bf16 v[192:195], v[40:43], v[140:143], v[184:187]
	v_mfma_f32_16x16x32_bf16 v[188:191], v[44:47], v[144:147], v[188:191]
	v_mfma_f32_16x16x32_bf16 v[192:195], v[36:39], v[144:147], v[192:195]
	v_exp_f32_e32 v196, v196
	v_exp_f32_e32 v197, v197
	v_exp_f32_e32 v198, v198
	v_exp_f32_e32 v199, v199
	v_mfma_f32_16x16x32_bf16 v[112:115], v[16:19], v[246:249], v[112:115]
	v_exp_f32_e32 v200, v200
	v_exp_f32_e32 v201, v201
	v_exp_f32_e32 v202, v202
	v_exp_f32_e32 v203, v203
	v_mfma_f32_16x16x32_bf16 v[108:111], v[12:15], v[246:249], v[108:111]
	v_cvt_pk_bf16_f32 v92, v196, v197
	v_cvt_pk_bf16_f32 v93, v198, v199
	v_cvt_pk_bf16_f32 v94, v200, v201
	v_cvt_pk_bf16_f32 v95, v202, v203
	v_mfma_f32_16x16x32_bf16 v[104:107], v[8:11], v[246:249], v[104:107]
	v_add_f32_e32 v196, v196, v197
	v_add_f32_e32 v198, v198, v199
	v_add_f32_e32 v200, v200, v201
	v_add_f32_e32 v202, v202, v203
	v_mfma_f32_16x16x32_bf16 v[100:103], v[4:7], v[246:249], v[100:103]
	v_add_f32_e32 v196, v196, v198
	v_add_f32_e32 v200, v200, v202
	v_add_f32_e32 v196, v196, v200
	v_add_f32_e32 v224, v224, v196
	v_mfma_f32_16x16x32_bf16 v[196:199], v[48:51], v[132:135], v[80:83]
	v_mfma_f32_16x16x32_bf16 v[200:203], v[40:43], v[132:135], v[84:87]
	v_mfma_f32_16x16x32_bf16 v[196:199], v[44:47], v[136:139], v[196:199]
	v_mfma_f32_16x16x32_bf16 v[200:203], v[36:39], v[136:139], v[200:203]
	v_exp_f32_e32 v188, v188
	v_exp_f32_e32 v189, v189
	v_exp_f32_e32 v190, v190
	v_exp_f32_e32 v191, v191
	v_mfma_f32_16x16x32_bf16 v[128:131], v[16:19], v[92:95], v[128:131]
	v_exp_f32_e32 v192, v192
	v_exp_f32_e32 v193, v193
	v_exp_f32_e32 v194, v194
	v_exp_f32_e32 v195, v195
	v_mfma_f32_16x16x32_bf16 v[124:127], v[12:15], v[92:95], v[124:127]
	v_cvt_pk_bf16_f32 v246, v188, v189
	v_cvt_pk_bf16_f32 v247, v190, v191
	v_cvt_pk_bf16_f32 v248, v192, v193
	v_cvt_pk_bf16_f32 v249, v194, v195
	v_mfma_f32_16x16x32_bf16 v[120:123], v[8:11], v[92:95], v[120:123]
	v_add_f32_e32 v188, v188, v189
	v_add_f32_e32 v190, v190, v191
	v_add_f32_e32 v192, v192, v193
	v_add_f32_e32 v194, v194, v195
	v_mfma_f32_16x16x32_bf16 v[116:119], v[4:7], v[92:95], v[116:119]
	v_add_f32_e32 v188, v188, v190
	v_add_f32_e32 v192, v192, v194
	v_add_f32_e32 v188, v188, v192
	v_add_f32_e32 v223, v223, v188
	v_exp_f32_e32 v196, v196
	v_exp_f32_e32 v197, v197
	v_exp_f32_e32 v198, v198
	v_exp_f32_e32 v199, v199
	v_mfma_f32_16x16x32_bf16 v[64:67], v[16:19], v[246:249], v[64:67]
	v_exp_f32_e32 v200, v200
	v_exp_f32_e32 v201, v201
	v_exp_f32_e32 v202, v202
	v_exp_f32_e32 v203, v203
	v_mfma_f32_16x16x32_bf16 v[60:63], v[12:15], v[246:249], v[60:63]
	v_cvt_pk_bf16_f32 v92, v196, v197
	v_cvt_pk_bf16_f32 v93, v198, v199
	v_cvt_pk_bf16_f32 v94, v200, v201
	v_cvt_pk_bf16_f32 v95, v202, v203
	v_mfma_f32_16x16x32_bf16 v[56:59], v[8:11], v[246:249], v[56:59]
	v_add_f32_e32 v196, v196, v197
	v_add_f32_e32 v198, v198, v199
	v_add_f32_e32 v200, v200, v201
	v_add_f32_e32 v202, v202, v203
	v_mfma_f32_16x16x32_bf16 v[52:55], v[4:7], v[246:249], v[52:55]
	v_add_f32_e32 v196, v196, v198
	v_add_f32_e32 v200, v200, v202
	v_add_f32_e32 v196, v196, v200
	v_add_f32_e32 v222, v222, v196
	v_mfma_f32_16x16x32_bf16 v[96:99], v[16:19], v[92:95], v[96:99]
	v_mfma_f32_16x16x32_bf16 v[88:91], v[12:15], v[92:95], v[88:91]
	v_mfma_f32_16x16x32_bf16 v[72:75], v[8:11], v[92:95], v[72:75]
	v_mfma_f32_16x16x32_bf16 v[68:71], v[4:7], v[92:95], v[68:71]
	v_add_u32_e32 v240, 0x100, v240
	s_waitcnt lgkmcnt(0)
	s_waitcnt vmcnt(0)
	s_cmp_gt_i32 s63, -2
	s_cbranch_scc0 .Latt_eb13
	s_barrier

.Latt_dk14:
	s_add_u32 s95, s95, 0x20000
	s_add_u32 s92, s92, 0x100
	s_sub_i32 s63, s63, 2
	ds_read_b128 v[48:51], v2 offset:0
	ds_read_b128 v[40:43], v2 offset:4096
	ds_read_b128 v[44:47], v2 offset:2048
	ds_read_b128 v[36:39], v2 offset:6144
	ds_read_b128 v[16:19], v235 offset:0
	ds_read_b128 v[12:15], v235 offset:2048
	ds_read_b128 v[8:11], v235 offset:4096
	ds_read_b128 v[4:7], v235 offset:6144
	v_mfma_f32_16x16x32_bf16 v[188:191], v[176:179], v[156:159], v[212:215]
	v_mfma_f32_16x16x32_bf16 v[192:195], v[168:171], v[156:159], v[242:245]
	v_mfma_f32_16x16x32_bf16 v[188:191], v[172:175], v[160:163], v[188:191]
	v_mfma_f32_16x16x32_bf16 v[192:195], v[164:167], v[160:163], v[192:195]
	v_mfma_f32_16x16x32_bf16 v[196:199], v[176:179], v[148:151], v[180:183]
	v_mfma_f32_16x16x32_bf16 v[200:203], v[168:171], v[148:151], v[184:187]
	v_mfma_f32_16x16x32_bf16 v[196:199], v[172:175], v[152:155], v[196:199]
	v_mfma_f32_16x16x32_bf16 v[200:203], v[164:167], v[152:155], v[200:203]
	s_nop 2
	v_exp_f32_e32 v188, v188
	v_exp_f32_e32 v189, v189
	v_exp_f32_e32 v190, v190
	v_exp_f32_e32 v191, v191
	v_exp_f32_e32 v192, v192
	v_exp_f32_e32 v193, v193
	v_exp_f32_e32 v194, v194
	v_exp_f32_e32 v195, v195
	v_cvt_pk_bf16_f32 v246, v188, v189
	v_cvt_pk_bf16_f32 v247, v190, v191
	v_cvt_pk_bf16_f32 v248, v192, v193
	v_cvt_pk_bf16_f32 v249, v194, v195
	v_add_f32_e32 v188, v188, v189
	v_add_f32_e32 v190, v190, v191
	v_add_f32_e32 v192, v192, v193
	v_add_f32_e32 v194, v194, v195
	v_add_f32_e32 v188, v188, v190
	v_add_f32_e32 v192, v192, v194
	v_add_f32_e32 v188, v188, v192
	v_add_f32_e32 v225, v225, v188
	v_mfma_f32_16x16x32_bf16 v[188:191], v[176:179], v[140:143], v[80:83]
	v_mfma_f32_16x16x32_bf16 v[192:195], v[168:171], v[140:143], v[84:87]
	v_mfma_f32_16x16x32_bf16 v[188:191], v[172:175], v[144:147], v[188:191]
	v_mfma_f32_16x16x32_bf16 v[192:195], v[164:167], v[144:147], v[192:195]
	v_exp_f32_e32 v196, v196
	v_exp_f32_e32 v197, v197
	v_exp_f32_e32 v198, v198
	v_exp_f32_e32 v199, v199
	v_mfma_f32_16x16x32_bf16 v[112:115], v[32:35], v[246:249], v[112:115]
	v_exp_f32_e32 v200, v200
	v_exp_f32_e32 v201, v201
	v_exp_f32_e32 v202, v202
	v_exp_f32_e32 v203, v203
	v_mfma_f32_16x16x32_bf16 v[108:111], v[28:31], v[246:249], v[108:111]
	v_cvt_pk_bf16_f32 v92, v196, v197
	v_cvt_pk_bf16_f32 v93, v198, v199
	v_cvt_pk_bf16_f32 v94, v200, v201
	v_cvt_pk_bf16_f32 v95, v202, v203
	v_mfma_f32_16x16x32_bf16 v[104:107], v[24:27], v[246:249], v[104:107]
	v_add_f32_e32 v196, v196, v197
	v_add_f32_e32 v198, v198, v199
	v_add_f32_e32 v200, v200, v201
	v_add_f32_e32 v202, v202, v203
	v_mfma_f32_16x16x32_bf16 v[100:103], v[20:23], v[246:249], v[100:103]
	v_add_f32_e32 v196, v196, v198
	v_add_f32_e32 v200, v200, v202
	v_add_f32_e32 v196, v196, v200
	v_add_f32_e32 v224, v224, v196
	v_exp_f32_e32 v188, v188
	v_exp_f32_e32 v189, v189
	v_exp_f32_e32 v190, v190
	v_exp_f32_e32 v191, v191
	v_mfma_f32_16x16x32_bf16 v[128:131], v[32:35], v[92:95], v[128:131]
	v_exp_f32_e32 v192, v192
	v_exp_f32_e32 v193, v193
	v_exp_f32_e32 v194, v194
	v_exp_f32_e32 v195, v195
	v_mfma_f32_16x16x32_bf16 v[124:127], v[28:31], v[92:95], v[124:127]
	v_cvt_pk_bf16_f32 v246, v188, v189
	v_cvt_pk_bf16_f32 v247, v190, v191
	v_cvt_pk_bf16_f32 v248, v192, v193
	v_cvt_pk_bf16_f32 v249, v194, v195
	v_mfma_f32_16x16x32_bf16 v[120:123], v[24:27], v[92:95], v[120:123]
	v_add_f32_e32 v188, v188, v189
	v_add_f32_e32 v190, v190, v191
	v_add_f32_e32 v192, v192, v193
	v_add_f32_e32 v194, v194, v195
	v_mfma_f32_16x16x32_bf16 v[116:119], v[20:23], v[92:95], v[116:119]
	v_add_f32_e32 v188, v188, v190
	v_add_f32_e32 v192, v192, v194
	v_add_f32_e32 v188, v188, v192
	v_add_f32_e32 v223, v223, v188
	v_mfma_f32_16x16x32_bf16 v[64:67], v[32:35], v[246:249], v[64:67]
	v_mfma_f32_16x16x32_bf16 v[60:63], v[28:31], v[246:249], v[60:63]
	v_mfma_f32_16x16x32_bf16 v[56:59], v[24:27], v[246:249], v[56:59]
	v_mfma_f32_16x16x32_bf16 v[52:55], v[20:23], v[246:249], v[52:55]
	v_add_u32_e32 v240, 0x100, v240
	s_waitcnt lgkmcnt(0)
	ds_read_b128 v[176:179], v3 offset:0
	ds_read_b128 v[168:171], v3 offset:4096
	ds_read_b128 v[172:175], v3 offset:2048
	ds_read_b128 v[164:167], v3 offset:6144
	ds_read_b128 v[32:35], v250 offset:0
	ds_read_b128 v[28:31], v250 offset:2048
	ds_read_b128 v[24:27], v250 offset:4096
	ds_read_b128 v[20:23], v250 offset:6144
	v_mfma_f32_16x16x32_bf16 v[188:191], v[48:51], v[156:159], v[180:183]
	v_mfma_f32_16x16x32_bf16 v[192:195], v[40:43], v[156:159], v[184:187]
	v_mfma_f32_16x16x32_bf16 v[188:191], v[44:47], v[160:163], v[188:191]
	v_mfma_f32_16x16x32_bf16 v[192:195], v[36:39], v[160:163], v[192:195]
	v_mfma_f32_16x16x32_bf16 v[196:199], v[48:51], v[148:151], v[80:83]
	v_mfma_f32_16x16x32_bf16 v[200:203], v[40:43], v[148:151], v[84:87]
	v_mfma_f32_16x16x32_bf16 v[196:199], v[44:47], v[152:155], v[196:199]
	v_mfma_f32_16x16x32_bf16 v[200:203], v[36:39], v[152:155], v[200:203]
	s_nop 2
	v_exp_f32_e32 v188, v188
	v_exp_f32_e32 v189, v189
	v_exp_f32_e32 v190, v190
	v_exp_f32_e32 v191, v191
	v_exp_f32_e32 v192, v192
	v_exp_f32_e32 v193, v193
	v_exp_f32_e32 v194, v194
	v_exp_f32_e32 v195, v195
	v_cvt_pk_bf16_f32 v246, v188, v189
	v_cvt_pk_bf16_f32 v247, v190, v191
	v_cvt_pk_bf16_f32 v248, v192, v193
	v_cvt_pk_bf16_f32 v249, v194, v195
	v_add_f32_e32 v188, v188, v189
	v_add_f32_e32 v190, v190, v191
	v_add_f32_e32 v192, v192, v193
	v_add_f32_e32 v194, v194, v195
	v_add_f32_e32 v188, v188, v190
	v_add_f32_e32 v192, v192, v194
	v_add_f32_e32 v188, v188, v192
	v_add_f32_e32 v225, v225, v188
	v_exp_f32_e32 v196, v196
	v_exp_f32_e32 v197, v197
	v_exp_f32_e32 v198, v198
	v_exp_f32_e32 v199, v199
	v_mfma_f32_16x16x32_bf16 v[112:115], v[16:19], v[246:249], v[112:115]
	v_exp_f32_e32 v200, v200
	v_exp_f32_e32 v201, v201
	v_exp_f32_e32 v202, v202
	v_exp_f32_e32 v203, v203
	v_mfma_f32_16x16x32_bf16 v[108:111], v[12:15], v[246:249], v[108:111]
	v_cvt_pk_bf16_f32 v92, v196, v197
	v_cvt_pk_bf16_f32 v93, v198, v199
	v_cvt_pk_bf16_f32 v94, v200, v201
	v_cvt_pk_bf16_f32 v95, v202, v203
	v_mfma_f32_16x16x32_bf16 v[104:107], v[8:11], v[246:249], v[104:107]
	v_add_f32_e32 v196, v196, v197
	v_add_f32_e32 v198, v198, v199
	v_add_f32_e32 v200, v200, v201
	v_add_f32_e32 v202, v202, v203
	v_mfma_f32_16x16x32_bf16 v[100:103], v[4:7], v[246:249], v[100:103]
	v_add_f32_e32 v196, v196, v198
	v_add_f32_e32 v200, v200, v202
	v_add_f32_e32 v196, v196, v200
	v_add_f32_e32 v224, v224, v196
	v_mfma_f32_16x16x32_bf16 v[128:131], v[16:19], v[92:95], v[128:131]
	v_mfma_f32_16x16x32_bf16 v[124:127], v[12:15], v[92:95], v[124:127]
	v_mfma_f32_16x16x32_bf16 v[120:123], v[8:11], v[92:95], v[120:123]
	v_mfma_f32_16x16x32_bf16 v[116:119], v[4:7], v[92:95], v[116:119]
	v_add_u32_e32 v240, 0x100, v240
	s_waitcnt lgkmcnt(0)
	s_waitcnt vmcnt(0)
	s_cmp_gt_i32 s63, -2
	s_cbranch_scc0 .Latt_eb15
	s_barrier

.Latt_dk16:
	s_add_u32 s95, s95, 0x20000
	s_add_u32 s92, s92, 0x100
	s_sub_i32 s63, s63, 2
	s_lshl_b32 s20, s60, 13
	s_add_u32 s23, s20, 0x8000
	s_add_u32 s33, s20, 0xa000
	v_add_u32_e32 v251, s23, v233
	v_add_u32_e32 v253, s33, v234
	ds_read_b128 v[48:51], v251 offset:0
	ds_read_b128 v[40:43], v251 offset:4096
	ds_read_b128 v[44:47], v251 offset:2048
	ds_read_b128 v[36:39], v251 offset:6144
	ds_read_b128 v[16:19], v253 offset:0
	ds_read_b128 v[12:15], v253 offset:2048
	ds_read_b128 v[8:11], v253 offset:4096
	ds_read_b128 v[4:7], v253 offset:6144
	v_mfma_f32_16x16x32_bf16 v[188:191], v[176:179], v[156:159], v[80:83]
	v_mfma_f32_16x16x32_bf16 v[192:195], v[168:171], v[156:159], v[84:87]
	v_mfma_f32_16x16x32_bf16 v[188:191], v[172:175], v[160:163], v[188:191]
	v_mfma_f32_16x16x32_bf16 v[192:195], v[164:167], v[160:163], v[192:195]
	s_nop 6
	v_exp_f32_e32 v188, v188
	v_exp_f32_e32 v189, v189
	v_exp_f32_e32 v190, v190
	v_exp_f32_e32 v191, v191
	v_exp_f32_e32 v192, v192
	v_exp_f32_e32 v193, v193
	v_exp_f32_e32 v194, v194
	v_exp_f32_e32 v195, v195
	v_cvt_pk_bf16_f32 v246, v188, v189
	v_cvt_pk_bf16_f32 v247, v190, v191
	v_cvt_pk_bf16_f32 v248, v192, v193
	v_cvt_pk_bf16_f32 v249, v194, v195
	v_add_f32_e32 v188, v188, v189
	v_add_f32_e32 v190, v190, v191
	v_add_f32_e32 v192, v192, v193
	v_add_f32_e32 v194, v194, v195
	v_add_f32_e32 v188, v188, v190
	v_add_f32_e32 v192, v192, v194
	v_add_f32_e32 v188, v188, v192
	v_add_f32_e32 v225, v225, v188
	v_mfma_f32_16x16x32_bf16 v[112:115], v[32:35], v[246:249], v[112:115]
	v_mfma_f32_16x16x32_bf16 v[108:111], v[28:31], v[246:249], v[108:111]
	v_mfma_f32_16x16x32_bf16 v[104:107], v[24:27], v[246:249], v[104:107]
	v_mfma_f32_16x16x32_bf16 v[100:103], v[20:23], v[246:249], v[100:103]
	v_add_u32_e32 v240, 0x100, v240
	s_sub_u32 s91, 8, s60
	s_branch .Latt_CB

.Latt_F0:
	s_waitcnt lgkmcnt(0)
	s_waitcnt vmcnt(0)
	s_cmp_gt_i32 s63, -2
	s_cbranch_scc0 .Latt_eb17
	s_barrier

.Latt_dk20:
	s_add_u32 s95, s95, 0x20000
	s_add_u32 s92, s92, 0x100
	s_sub_i32 s63, s63, 2
	ds_read_b128 v[48:51], v220 offset:0
	ds_read_b128 v[40:43], v220 offset:4096
	ds_read_b128 v[44:47], v220 offset:2048
	ds_read_b128 v[36:39], v220 offset:6144
	ds_read_b128 v[16:19], v254 offset:0
	ds_read_b128 v[12:15], v254 offset:2048
	ds_read_b128 v[8:11], v254 offset:4096
	ds_read_b128 v[4:7], v254 offset:6144
	v_mfma_f32_16x16x32_bf16 v[188:191], v[176:179], v[156:159], v[80:83]
	v_mfma_f32_16x16x32_bf16 v[192:195], v[168:171], v[156:159], v[84:87]
	v_mfma_f32_16x16x32_bf16 v[188:191], v[172:175], v[160:163], v[188:191]
	v_mfma_f32_16x16x32_bf16 v[192:195], v[164:167], v[160:163], v[192:195]
	ds_read2_b32 v[80:81], v240 offset0:0 offset1:1
	ds_read2_b32 v[82:83], v240 offset0:2 offset1:3
	ds_read2_b32 v[84:85], v240 offset0:4 offset1:5
	ds_read2_b32 v[86:87], v240 offset0:6 offset1:7
	v_mfma_f32_16x16x32_bf16 v[196:199], v[176:179], v[148:151], v[204:207]
	v_mfma_f32_16x16x32_bf16 v[200:203], v[168:171], v[148:151], v[208:211]
	v_mfma_f32_16x16x32_bf16 v[196:199], v[172:175], v[152:155], v[196:199]
	v_mfma_f32_16x16x32_bf16 v[200:203], v[164:167], v[152:155], v[200:203]
	v_exp_f32_e32 v188, v188
	v_exp_f32_e32 v189, v189
	v_exp_f32_e32 v190, v190
	v_exp_f32_e32 v191, v191
	v_exp_f32_e32 v192, v192
	v_exp_f32_e32 v193, v193
	v_exp_f32_e32 v194, v194
	v_exp_f32_e32 v195, v195
	v_cvt_pk_bf16_f32 v246, v188, v189
	v_cvt_pk_bf16_f32 v247, v190, v191
	v_cvt_pk_bf16_f32 v248, v192, v193
	v_cvt_pk_bf16_f32 v249, v194, v195
	v_add_f32_e32 v188, v188, v189
	v_add_f32_e32 v190, v190, v191
	v_add_f32_e32 v192, v192, v193
	v_add_f32_e32 v194, v194, v195
	v_add_f32_e32 v188, v188, v190
	v_add_f32_e32 v192, v192, v194
	v_add_f32_e32 v188, v188, v192
	v_add_f32_e32 v225, v225, v188
	v_mfma_f32_16x16x32_bf16 v[188:191], v[176:179], v[140:143], v[212:215]
	v_mfma_f32_16x16x32_bf16 v[192:195], v[168:171], v[140:143], v[242:245]
	v_mfma_f32_16x16x32_bf16 v[188:191], v[172:175], v[144:147], v[188:191]
	v_mfma_f32_16x16x32_bf16 v[192:195], v[164:167], v[144:147], v[192:195]
	v_exp_f32_e32 v196, v196
	v_exp_f32_e32 v197, v197
	v_exp_f32_e32 v198, v198
	v_exp_f32_e32 v199, v199
	v_mfma_f32_16x16x32_bf16 v[112:115], v[32:35], v[246:249], v[112:115]
	v_exp_f32_e32 v200, v200
	v_exp_f32_e32 v201, v201
	v_exp_f32_e32 v202, v202
	v_exp_f32_e32 v203, v203
	v_mfma_f32_16x16x32_bf16 v[108:111], v[28:31], v[246:249], v[108:111]
	v_cvt_pk_bf16_f32 v92, v196, v197
	v_cvt_pk_bf16_f32 v93, v198, v199
	v_cvt_pk_bf16_f32 v94, v200, v201
	v_cvt_pk_bf16_f32 v95, v202, v203
	v_mfma_f32_16x16x32_bf16 v[104:107], v[24:27], v[246:249], v[104:107]
	v_add_f32_e32 v196, v196, v197
	v_add_f32_e32 v198, v198, v199
	v_add_f32_e32 v200, v200, v201
	v_add_f32_e32 v202, v202, v203
	v_mfma_f32_16x16x32_bf16 v[100:103], v[20:23], v[246:249], v[100:103]
	v_add_f32_e32 v196, v196, v198
	v_add_f32_e32 v200, v200, v202
	v_add_f32_e32 v196, v196, v200
	v_add_f32_e32 v224, v224, v196
	v_mfma_f32_16x16x32_bf16 v[196:199], v[176:179], v[132:135], v[180:183]
	v_mfma_f32_16x16x32_bf16 v[200:203], v[168:171], v[132:135], v[184:187]
	v_mfma_f32_16x16x32_bf16 v[196:199], v[172:175], v[136:139], v[196:199]
	v_mfma_f32_16x16x32_bf16 v[200:203], v[164:167], v[136:139], v[200:203]
	v_exp_f32_e32 v188, v188
	v_exp_f32_e32 v189, v189
	v_exp_f32_e32 v190, v190
	v_exp_f32_e32 v191, v191
	v_mfma_f32_16x16x32_bf16 v[128:131], v[32:35], v[92:95], v[128:131]
	v_exp_f32_e32 v192, v192
	v_exp_f32_e32 v193, v193
	v_exp_f32_e32 v194, v194
	v_exp_f32_e32 v195, v195
	v_mfma_f32_16x16x32_bf16 v[124:127], v[28:31], v[92:95], v[124:127]
	v_cvt_pk_bf16_f32 v246, v188, v189
	v_cvt_pk_bf16_f32 v247, v190, v191
	v_cvt_pk_bf16_f32 v248, v192, v193
	v_cvt_pk_bf16_f32 v249, v194, v195
	v_mfma_f32_16x16x32_bf16 v[120:123], v[24:27], v[92:95], v[120:123]
	v_add_f32_e32 v188, v188, v189
	v_add_f32_e32 v190, v190, v191
	v_add_f32_e32 v192, v192, v193
	v_add_f32_e32 v194, v194, v195
	v_mfma_f32_16x16x32_bf16 v[116:119], v[20:23], v[92:95], v[116:119]
	v_add_f32_e32 v188, v188, v190
	v_add_f32_e32 v192, v192, v194
	v_add_f32_e32 v188, v188, v192
	v_add_f32_e32 v223, v223, v188
	v_exp_f32_e32 v196, v196
	v_exp_f32_e32 v197, v197
	v_exp_f32_e32 v198, v198
	v_exp_f32_e32 v199, v199
	v_mfma_f32_16x16x32_bf16 v[64:67], v[32:35], v[246:249], v[64:67]
	v_exp_f32_e32 v200, v200
	v_exp_f32_e32 v201, v201
	v_exp_f32_e32 v202, v202
	v_exp_f32_e32 v203, v203
	v_mfma_f32_16x16x32_bf16 v[60:63], v[28:31], v[246:249], v[60:63]
	v_cvt_pk_bf16_f32 v92, v196, v197
	v_cvt_pk_bf16_f32 v93, v198, v199
	v_cvt_pk_bf16_f32 v94, v200, v201
	v_cvt_pk_bf16_f32 v95, v202, v203
	v_mfma_f32_16x16x32_bf16 v[56:59], v[24:27], v[246:249], v[56:59]
	v_add_f32_e32 v196, v196, v197
	v_add_f32_e32 v198, v198, v199
	v_add_f32_e32 v200, v200, v201
	v_add_f32_e32 v202, v202, v203
	v_mfma_f32_16x16x32_bf16 v[52:55], v[20:23], v[246:249], v[52:55]
	v_add_f32_e32 v196, v196, v198
	v_add_f32_e32 v200, v200, v202
	v_add_f32_e32 v196, v196, v200
	v_add_f32_e32 v222, v222, v196
	s_waitcnt lgkmcnt(0)
	v_sub_f32_e32 v80, v80, v239
	v_sub_f32_e32 v81, v81, v239
	v_sub_f32_e32 v82, v82, v239
	v_mfma_f32_16x16x32_bf16 v[96:99], v[32:35], v[92:95], v[96:99]
	v_sub_f32_e32 v83, v83, v239
	v_sub_f32_e32 v84, v84, v239
	v_sub_f32_e32 v85, v85, v239
	v_mfma_f32_16x16x32_bf16 v[88:91], v[28:31], v[92:95], v[88:91]
	v_sub_f32_e32 v86, v86, v239
	v_sub_f32_e32 v87, v87, v239
	v_cndmask_b32_e64 v80, v238, v80, s[0:1]
	v_mfma_f32_16x16x32_bf16 v[72:75], v[24:27], v[92:95], v[72:75]
	v_cndmask_b32_e64 v81, v238, v81, s[6:7]
	v_cndmask_b32_e64 v82, v238, v82, s[8:9]
	v_cndmask_b32_e64 v83, v238, v83, s[10:11]
	v_mfma_f32_16x16x32_bf16 v[68:71], v[20:23], v[92:95], v[68:71]
	v_cndmask_b32_e64 v84, v238, v84, s[12:13]
	v_cndmask_b32_e64 v85, v238, v85, s[14:15]
	v_cndmask_b32_e64 v86, v238, v86, s[16:17]
	v_cndmask_b32_e64 v87, v238, v87, s[18:19]
	v_add_u32_e32 v240, 0x100, v240
	s_waitcnt lgkmcnt(0)
	s_cmp_eq_u32 s91, 1
	s_cbranch_scc1 .Latt_wc21
	ds_read_b128 v[176:179], v1 offset:0
	ds_read_b128 v[168:171], v1 offset:4096
	ds_read_b128 v[172:175], v1 offset:2048
	ds_read_b128 v[164:167], v1 offset:6144
	ds_read_b128 v[32:35], v221 offset:0
	ds_read_b128 v[28:31], v221 offset:2048
	ds_read_b128 v[24:27], v221 offset:4096
	ds_read_b128 v[20:23], v221 offset:6144
	s_branch .Latt_we21
.Latt_wc21:
	s_lshl_b32 s20, s60, 13
	s_add_u32 s23, s20, 0x8000
	s_add_u32 s33, s20, 0xa000
	v_add_u32_e32 v251, s23, v233
	v_add_u32_e32 v253, s33, v234
	ds_read_b128 v[176:179], v251 offset:0
	ds_read_b128 v[168:171], v251 offset:4096
	ds_read_b128 v[172:175], v251 offset:2048
	ds_read_b128 v[164:167], v251 offset:6144
	ds_read_b128 v[32:35], v253 offset:0
	ds_read_b128 v[28:31], v253 offset:2048
	ds_read_b128 v[24:27], v253 offset:4096
	ds_read_b128 v[20:23], v253 offset:6144
.Latt_we21:
	v_mfma_f32_16x16x32_bf16 v[188:191], v[48:51], v[156:159], v[204:207]
	v_mfma_f32_16x16x32_bf16 v[192:195], v[40:43], v[156:159], v[208:211]
	v_mfma_f32_16x16x32_bf16 v[188:191], v[44:47], v[160:163], v[188:191]
	v_mfma_f32_16x16x32_bf16 v[192:195], v[36:39], v[160:163], v[192:195]
	ds_read2_b32 v[204:205], v240 offset0:0 offset1:1
	ds_read2_b32 v[206:207], v240 offset0:2 offset1:3
	ds_read2_b32 v[208:209], v240 offset0:4 offset1:5
	ds_read2_b32 v[210:211], v240 offset0:6 offset1:7
	v_mfma_f32_16x16x32_bf16 v[196:199], v[48:51], v[148:151], v[212:215]
	v_mfma_f32_16x16x32_bf16 v[200:203], v[40:43], v[148:151], v[242:245]
	v_mfma_f32_16x16x32_bf16 v[196:199], v[44:47], v[152:155], v[196:199]
	v_mfma_f32_16x16x32_bf16 v[200:203], v[36:39], v[152:155], v[200:203]
	v_exp_f32_e32 v188, v188
	v_exp_f32_e32 v189, v189
	v_exp_f32_e32 v190, v190
	v_exp_f32_e32 v191, v191
	v_exp_f32_e32 v192, v192
	v_exp_f32_e32 v193, v193
	v_exp_f32_e32 v194, v194
	v_exp_f32_e32 v195, v195
	v_cvt_pk_bf16_f32 v246, v188, v189
	v_cvt_pk_bf16_f32 v247, v190, v191
	v_cvt_pk_bf16_f32 v248, v192, v193
	v_cvt_pk_bf16_f32 v249, v194, v195
	v_add_f32_e32 v188, v188, v189
	v_add_f32_e32 v190, v190, v191
	v_add_f32_e32 v192, v192, v193
	v_add_f32_e32 v194, v194, v195
	v_add_f32_e32 v188, v188, v190
	v_add_f32_e32 v192, v192, v194
	v_add_f32_e32 v188, v188, v192
	v_add_f32_e32 v225, v225, v188
	v_mfma_f32_16x16x32_bf16 v[188:191], v[48:51], v[140:143], v[180:183]
	v_mfma_f32_16x16x32_bf16 v[192:195], v[40:43], v[140:143], v[184:187]
	v_mfma_f32_16x16x32_bf16 v[188:191], v[44:47], v[144:147], v[188:191]
	v_mfma_f32_16x16x32_bf16 v[192:195], v[36:39], v[144:147], v[192:195]
	v_exp_f32_e32 v196, v196
	v_exp_f32_e32 v197, v197
	v_exp_f32_e32 v198, v198
	v_exp_f32_e32 v199, v199
	v_mfma_f32_16x16x32_bf16 v[112:115], v[16:19], v[246:249], v[112:115]
	v_exp_f32_e32 v200, v200
	v_exp_f32_e32 v201, v201
	v_exp_f32_e32 v202, v202
	v_exp_f32_e32 v203, v203
	v_mfma_f32_16x16x32_bf16 v[108:111], v[12:15], v[246:249], v[108:111]
	v_cvt_pk_bf16_f32 v92, v196, v197
	v_cvt_pk_bf16_f32 v93, v198, v199
	v_cvt_pk_bf16_f32 v94, v200, v201
	v_cvt_pk_bf16_f32 v95, v202, v203
	v_mfma_f32_16x16x32_bf16 v[104:107], v[8:11], v[246:249], v[104:107]
	v_add_f32_e32 v196, v196, v197
	v_add_f32_e32 v198, v198, v199
	v_add_f32_e32 v200, v200, v201
	v_add_f32_e32 v202, v202, v203
	v_mfma_f32_16x16x32_bf16 v[100:103], v[4:7], v[246:249], v[100:103]
	v_add_f32_e32 v196, v196, v198
	v_add_f32_e32 v200, v200, v202
	v_add_f32_e32 v196, v196, v200
	v_add_f32_e32 v224, v224, v196
	v_mfma_f32_16x16x32_bf16 v[196:199], v[48:51], v[132:135], v[80:83]
	v_mfma_f32_16x16x32_bf16 v[200:203], v[40:43], v[132:135], v[84:87]
	v_mfma_f32_16x16x32_bf16 v[196:199], v[44:47], v[136:139], v[196:199]
	v_mfma_f32_16x16x32_bf16 v[200:203], v[36:39], v[136:139], v[200:203]
	v_exp_f32_e32 v188, v188
	v_exp_f32_e32 v189, v189
	v_exp_f32_e32 v190, v190
	v_exp_f32_e32 v191, v191
	v_mfma_f32_16x16x32_bf16 v[128:131], v[16:19], v[92:95], v[128:131]
	v_exp_f32_e32 v192, v192
	v_exp_f32_e32 v193, v193
	v_exp_f32_e32 v194, v194
	v_exp_f32_e32 v195, v195
	v_mfma_f32_16x16x32_bf16 v[124:127], v[12:15], v[92:95], v[124:127]
	v_cvt_pk_bf16_f32 v246, v188, v189
	v_cvt_pk_bf16_f32 v247, v190, v191
	v_cvt_pk_bf16_f32 v248, v192, v193
	v_cvt_pk_bf16_f32 v249, v194, v195
	v_mfma_f32_16x16x32_bf16 v[120:123], v[8:11], v[92:95], v[120:123]
	v_add_f32_e32 v188, v188, v189
	v_add_f32_e32 v190, v190, v191
	v_add_f32_e32 v192, v192, v193
	v_add_f32_e32 v194, v194, v195
	v_mfma_f32_16x16x32_bf16 v[116:119], v[4:7], v[92:95], v[116:119]
	v_add_f32_e32 v188, v188, v190
	v_add_f32_e32 v192, v192, v194
	v_add_f32_e32 v188, v188, v192
	v_add_f32_e32 v223, v223, v188
	v_exp_f32_e32 v196, v196
	v_exp_f32_e32 v197, v197
	v_exp_f32_e32 v198, v198
	v_exp_f32_e32 v199, v199
	v_mfma_f32_16x16x32_bf16 v[64:67], v[16:19], v[246:249], v[64:67]
	v_exp_f32_e32 v200, v200
	v_exp_f32_e32 v201, v201
	v_exp_f32_e32 v202, v202
	v_exp_f32_e32 v203, v203
	v_mfma_f32_16x16x32_bf16 v[60:63], v[12:15], v[246:249], v[60:63]
	v_cvt_pk_bf16_f32 v92, v196, v197
	v_cvt_pk_bf16_f32 v93, v198, v199
	v_cvt_pk_bf16_f32 v94, v200, v201
	v_cvt_pk_bf16_f32 v95, v202, v203
	v_mfma_f32_16x16x32_bf16 v[56:59], v[8:11], v[246:249], v[56:59]
	v_add_f32_e32 v196, v196, v197
	v_add_f32_e32 v198, v198, v199
	v_add_f32_e32 v200, v200, v201
	v_add_f32_e32 v202, v202, v203
	v_mfma_f32_16x16x32_bf16 v[52:55], v[4:7], v[246:249], v[52:55]
	v_add_f32_e32 v196, v196, v198
	v_add_f32_e32 v200, v200, v202
	v_add_f32_e32 v196, v196, v200
	v_add_f32_e32 v222, v222, v196
	s_waitcnt lgkmcnt(0)
	v_sub_f32_e32 v204, v204, v239
	v_sub_f32_e32 v205, v205, v239
	v_sub_f32_e32 v206, v206, v239
	v_mfma_f32_16x16x32_bf16 v[96:99], v[16:19], v[92:95], v[96:99]
	v_sub_f32_e32 v207, v207, v239
	v_sub_f32_e32 v208, v208, v239
	v_sub_f32_e32 v209, v209, v239
	v_mfma_f32_16x16x32_bf16 v[88:91], v[12:15], v[92:95], v[88:91]
	v_sub_f32_e32 v210, v210, v239
	v_sub_f32_e32 v211, v211, v239
	v_cndmask_b32_e64 v204, v238, v204, s[0:1]
	v_mfma_f32_16x16x32_bf16 v[72:75], v[8:11], v[92:95], v[72:75]
	v_cndmask_b32_e64 v205, v238, v205, s[6:7]
	v_cndmask_b32_e64 v206, v238, v206, s[8:9]
	v_cndmask_b32_e64 v207, v238, v207, s[10:11]
	v_mfma_f32_16x16x32_bf16 v[68:71], v[4:7], v[92:95], v[68:71]
	v_cndmask_b32_e64 v208, v238, v208, s[12:13]
	v_cndmask_b32_e64 v209, v238, v209, s[14:15]
	v_cndmask_b32_e64 v210, v238, v210, s[16:17]
	v_cndmask_b32_e64 v211, v238, v211, s[18:19]
	v_add_u32_e32 v240, 0x100, v240
	s_sub_u32 s91, s91, 1
	s_cmp_lg_u32 s91, 0
	s_cbranch_scc1 .Latt_F0
	s_sub_u32 s91, 8, s60

.Latt_eb22:
	s_sub_i32 s63, s63, 2
	s_movk_i32 s20, 0x100
	s_movk_i32 s21, 0x400
	s_bitcmp1_b32 s23, 8
	s_cselect_b32 s20, 0x3f00, s20
	s_cselect_b32 s21, 0x3c00, s21
	s_add_u32 s23, s23, s20
	s_add_u32 s33, s33, s21
	v_add_u32_e32 v251, s23, v233
	v_add_u32_e32 v253, s33, v234
	ds_read_b128 v[48:51], v251 offset:0
	ds_read_b128 v[40:43], v251 offset:4096
	ds_read_b128 v[44:47], v251 offset:2048
	ds_read_b128 v[36:39], v251 offset:6144
	ds_read_b128 v[16:19], v253 offset:0
	ds_read_b128 v[12:15], v253 offset:2048
	ds_read_b128 v[8:11], v253 offset:4096
	ds_read_b128 v[4:7], v253 offset:6144
	v_mfma_f32_16x16x32_bf16 v[188:191], v[176:179], v[132:135], v[76:79]
	v_mfma_f32_16x16x32_bf16 v[192:195], v[168:171], v[132:135], v[76:79]
	v_mfma_f32_16x16x32_bf16 v[188:191], v[172:175], v[136:139], v[188:191]
	v_mfma_f32_16x16x32_bf16 v[192:195], v[164:167], v[136:139], v[192:195]
	v_mfma_f32_16x16x32_bf16 v[196:199], v[176:179], v[140:143], v[76:79]
	v_mfma_f32_16x16x32_bf16 v[200:203], v[168:171], v[140:143], v[76:79]
	v_mfma_f32_16x16x32_bf16 v[196:199], v[172:175], v[144:147], v[196:199]
	v_mfma_f32_16x16x32_bf16 v[200:203], v[164:167], v[144:147], v[200:203]
	s_nop 2
	v_exp_f32_e32 v188, v188
	v_exp_f32_e32 v189, v189
	v_exp_f32_e32 v190, v190
	v_exp_f32_e32 v191, v191
	v_exp_f32_e32 v192, v192
	v_exp_f32_e32 v193, v193
	v_exp_f32_e32 v194, v194
	v_exp_f32_e32 v195, v195
	v_cvt_pk_bf16_f32 v246, v188, v189
	v_cvt_pk_bf16_f32 v247, v190, v191
	v_cvt_pk_bf16_f32 v248, v192, v193
	v_cvt_pk_bf16_f32 v249, v194, v195
	v_add_f32_e32 v188, v188, v189
	v_add_f32_e32 v190, v190, v191
	v_add_f32_e32 v192, v192, v193
	v_add_f32_e32 v194, v194, v195
	v_add_f32_e32 v188, v188, v190
	v_add_f32_e32 v192, v192, v194
	v_add_f32_e32 v188, v188, v192
	v_add_f32_e32 v222, v222, v188
	v_mfma_f32_16x16x32_bf16 v[188:191], v[176:179], v[148:151], v[76:79]
	v_mfma_f32_16x16x32_bf16 v[192:195], v[168:171], v[148:151], v[76:79]
	v_mfma_f32_16x16x32_bf16 v[188:191], v[172:175], v[152:155], v[188:191]
	v_mfma_f32_16x16x32_bf16 v[192:195], v[164:167], v[152:155], v[192:195]
	v_exp_f32_e32 v196, v196
	v_exp_f32_e32 v197, v197
	v_exp_f32_e32 v198, v198
	v_exp_f32_e32 v199, v199
	v_mfma_f32_16x16x32_bf16 v[96:99], v[32:35], v[246:249], v[96:99]
	v_exp_f32_e32 v200, v200
	v_exp_f32_e32 v201, v201
	v_exp_f32_e32 v202, v202
	v_exp_f32_e32 v203, v203
	v_mfma_f32_16x16x32_bf16 v[88:91], v[28:31], v[246:249], v[88:91]
	v_cvt_pk_bf16_f32 v92, v196, v197
	v_cvt_pk_bf16_f32 v93, v198, v199
	v_cvt_pk_bf16_f32 v94, v200, v201
	v_cvt_pk_bf16_f32 v95, v202, v203
	v_mfma_f32_16x16x32_bf16 v[72:75], v[24:27], v[246:249], v[72:75]
	v_add_f32_e32 v196, v196, v197
	v_add_f32_e32 v198, v198, v199
	v_add_f32_e32 v200, v200, v201
	v_add_f32_e32 v202, v202, v203
	v_mfma_f32_16x16x32_bf16 v[68:71], v[20:23], v[246:249], v[68:71]
	v_add_f32_e32 v196, v196, v198
	v_add_f32_e32 v200, v200, v202
	v_add_f32_e32 v196, v196, v200
	v_add_f32_e32 v223, v223, v196
	v_mfma_f32_16x16x32_bf16 v[196:199], v[176:179], v[156:159], v[76:79]
	v_mfma_f32_16x16x32_bf16 v[200:203], v[168:171], v[156:159], v[76:79]
	v_mfma_f32_16x16x32_bf16 v[196:199], v[172:175], v[160:163], v[196:199]
	v_mfma_f32_16x16x32_bf16 v[200:203], v[164:167], v[160:163], v[200:203]
	v_exp_f32_e32 v188, v188
	v_exp_f32_e32 v189, v189
	v_exp_f32_e32 v190, v190
	v_exp_f32_e32 v191, v191
	v_mfma_f32_16x16x32_bf16 v[64:67], v[32:35], v[92:95], v[64:67]
	v_exp_f32_e32 v192, v192
	v_exp_f32_e32 v193, v193
	v_exp_f32_e32 v194, v194
	v_exp_f32_e32 v195, v195
	v_mfma_f32_16x16x32_bf16 v[60:63], v[28:31], v[92:95], v[60:63]
	v_cvt_pk_bf16_f32 v246, v188, v189
	v_cvt_pk_bf16_f32 v247, v190, v191
	v_cvt_pk_bf16_f32 v248, v192, v193
	v_cvt_pk_bf16_f32 v249, v194, v195
	v_mfma_f32_16x16x32_bf16 v[56:59], v[24:27], v[92:95], v[56:59]
	v_add_f32_e32 v188, v188, v189
	v_add_f32_e32 v190, v190, v191
	v_add_f32_e32 v192, v192, v193
	v_add_f32_e32 v194, v194, v195
	v_mfma_f32_16x16x32_bf16 v[52:55], v[20:23], v[92:95], v[52:55]
	v_add_f32_e32 v188, v188, v190
	v_add_f32_e32 v192, v192, v194
	v_add_f32_e32 v188, v188, v192
	v_add_f32_e32 v224, v224, v188
	v_exp_f32_e32 v196, v196
	v_exp_f32_e32 v197, v197
	v_exp_f32_e32 v198, v198
	v_exp_f32_e32 v199, v199
	v_mfma_f32_16x16x32_bf16 v[128:131], v[32:35], v[246:249], v[128:131]
	v_exp_f32_e32 v200, v200
	v_exp_f32_e32 v201, v201
	v_exp_f32_e32 v202, v202
	v_exp_f32_e32 v203, v203
	v_mfma_f32_16x16x32_bf16 v[124:127], v[28:31], v[246:249], v[124:127]
	v_cvt_pk_bf16_f32 v92, v196, v197
	v_cvt_pk_bf16_f32 v93, v198, v199
	v_cvt_pk_bf16_f32 v94, v200, v201
	v_cvt_pk_bf16_f32 v95, v202, v203
	v_mfma_f32_16x16x32_bf16 v[120:123], v[24:27], v[246:249], v[120:123]
	v_add_f32_e32 v196, v196, v197
	v_add_f32_e32 v198, v198, v199
	v_add_f32_e32 v200, v200, v201
	v_add_f32_e32 v202, v202, v203
	v_mfma_f32_16x16x32_bf16 v[116:119], v[20:23], v[246:249], v[116:119]
	v_add_f32_e32 v196, v196, v198
	v_add_f32_e32 v200, v200, v202
	v_add_f32_e32 v196, v196, v200
	v_add_f32_e32 v225, v225, v196
	v_mfma_f32_16x16x32_bf16 v[112:115], v[32:35], v[92:95], v[112:115]
	v_mfma_f32_16x16x32_bf16 v[108:111], v[28:31], v[92:95], v[108:111]
	v_mfma_f32_16x16x32_bf16 v[104:107], v[24:27], v[92:95], v[104:107]
	v_mfma_f32_16x16x32_bf16 v[100:103], v[20:23], v[92:95], v[100:103]
	s_sub_u32 s91, s91, 1
	s_cmp_eq_u32 s91, 0
	s_cbranch_scc1 .Latt_cdone
.Latt_CB:
	s_waitcnt lgkmcnt(0)
	s_movk_i32 s20, 0x100
	s_movk_i32 s21, 0x400
	s_bitcmp1_b32 s23, 8
	s_cselect_b32 s20, 0x3f00, s20
	s_cselect_b32 s21, 0x3c00, s21
	s_add_u32 s23, s23, s20
	s_add_u32 s33, s33, s21
	v_add_u32_e32 v251, s23, v233
	v_add_u32_e32 v253, s33, v234
	ds_read_b128 v[176:179], v251 offset:0
	ds_read_b128 v[168:171], v251 offset:4096
	ds_read_b128 v[172:175], v251 offset:2048
	ds_read_b128 v[164:167], v251 offset:6144
	ds_read_b128 v[32:35], v253 offset:0
	ds_read_b128 v[28:31], v253 offset:2048
	ds_read_b128 v[24:27], v253 offset:4096
	ds_read_b128 v[20:23], v253 offset:6144
	v_mfma_f32_16x16x32_bf16 v[188:191], v[48:51], v[132:135], v[76:79]
	v_mfma_f32_16x16x32_bf16 v[192:195], v[40:43], v[132:135], v[76:79]
	v_mfma_f32_16x16x32_bf16 v[188:191], v[44:47], v[136:139], v[188:191]
	v_mfma_f32_16x16x32_bf16 v[192:195], v[36:39], v[136:139], v[192:195]
	v_mfma_f32_16x16x32_bf16 v[196:199], v[48:51], v[140:143], v[76:79]
	v_mfma_f32_16x16x32_bf16 v[200:203], v[40:43], v[140:143], v[76:79]
	v_mfma_f32_16x16x32_bf16 v[196:199], v[44:47], v[144:147], v[196:199]
	v_mfma_f32_16x16x32_bf16 v[200:203], v[36:39], v[144:147], v[200:203]
	s_nop 2
	v_exp_f32_e32 v188, v188
	v_exp_f32_e32 v189, v189
	v_exp_f32_e32 v190, v190
	v_exp_f32_e32 v191, v191
	v_exp_f32_e32 v192, v192
	v_exp_f32_e32 v193, v193
	v_exp_f32_e32 v194, v194
	v_exp_f32_e32 v195, v195
	v_cvt_pk_bf16_f32 v246, v188, v189
	v_cvt_pk_bf16_f32 v247, v190, v191
	v_cvt_pk_bf16_f32 v248, v192, v193
	v_cvt_pk_bf16_f32 v249, v194, v195
	v_add_f32_e32 v188, v188, v189
	v_add_f32_e32 v190, v190, v191
	v_add_f32_e32 v192, v192, v193
	v_add_f32_e32 v194, v194, v195
	v_add_f32_e32 v188, v188, v190
	v_add_f32_e32 v192, v192, v194
	v_add_f32_e32 v188, v188, v192
	v_add_f32_e32 v222, v222, v188
	v_mfma_f32_16x16x32_bf16 v[188:191], v[48:51], v[148:151], v[76:79]
	v_mfma_f32_16x16x32_bf16 v[192:195], v[40:43], v[148:151], v[76:79]
	v_mfma_f32_16x16x32_bf16 v[188:191], v[44:47], v[152:155], v[188:191]
	v_mfma_f32_16x16x32_bf16 v[192:195], v[36:39], v[152:155], v[192:195]
	v_exp_f32_e32 v196, v196
	v_exp_f32_e32 v197, v197
	v_exp_f32_e32 v198, v198
	v_exp_f32_e32 v199, v199
	v_mfma_f32_16x16x32_bf16 v[96:99], v[16:19], v[246:249], v[96:99]
	v_exp_f32_e32 v200, v200
	v_exp_f32_e32 v201, v201
	v_exp_f32_e32 v202, v202
	v_exp_f32_e32 v203, v203
	v_mfma_f32_16x16x32_bf16 v[88:91], v[12:15], v[246:249], v[88:91]
	v_cvt_pk_bf16_f32 v92, v196, v197
	v_cvt_pk_bf16_f32 v93, v198, v199
	v_cvt_pk_bf16_f32 v94, v200, v201
	v_cvt_pk_bf16_f32 v95, v202, v203
	v_mfma_f32_16x16x32_bf16 v[72:75], v[8:11], v[246:249], v[72:75]
	v_add_f32_e32 v196, v196, v197
	v_add_f32_e32 v198, v198, v199
	v_add_f32_e32 v200, v200, v201
	v_add_f32_e32 v202, v202, v203
	v_mfma_f32_16x16x32_bf16 v[68:71], v[4:7], v[246:249], v[68:71]
	v_add_f32_e32 v196, v196, v198
	v_add_f32_e32 v200, v200, v202
	v_add_f32_e32 v196, v196, v200
	v_add_f32_e32 v223, v223, v196
	v_mfma_f32_16x16x32_bf16 v[196:199], v[48:51], v[156:159], v[76:79]
	v_mfma_f32_16x16x32_bf16 v[200:203], v[40:43], v[156:159], v[76:79]
	v_mfma_f32_16x16x32_bf16 v[196:199], v[44:47], v[160:163], v[196:199]
	v_mfma_f32_16x16x32_bf16 v[200:203], v[36:39], v[160:163], v[200:203]
	v_exp_f32_e32 v188, v188
	v_exp_f32_e32 v189, v189
	v_exp_f32_e32 v190, v190
	v_exp_f32_e32 v191, v191
	v_mfma_f32_16x16x32_bf16 v[64:67], v[16:19], v[92:95], v[64:67]
	v_exp_f32_e32 v192, v192
	v_exp_f32_e32 v193, v193
	v_exp_f32_e32 v194, v194
	v_exp_f32_e32 v195, v195
	v_mfma_f32_16x16x32_bf16 v[60:63], v[12:15], v[92:95], v[60:63]
	v_cvt_pk_bf16_f32 v246, v188, v189
	v_cvt_pk_bf16_f32 v247, v190, v191
	v_cvt_pk_bf16_f32 v248, v192, v193
	v_cvt_pk_bf16_f32 v249, v194, v195
	v_mfma_f32_16x16x32_bf16 v[56:59], v[8:11], v[92:95], v[56:59]
	v_add_f32_e32 v188, v188, v189
	v_add_f32_e32 v190, v190, v191
	v_add_f32_e32 v192, v192, v193
	v_add_f32_e32 v194, v194, v195
	v_mfma_f32_16x16x32_bf16 v[52:55], v[4:7], v[92:95], v[52:55]
	v_add_f32_e32 v188, v188, v190
	v_add_f32_e32 v192, v192, v194
	v_add_f32_e32 v188, v188, v192
	v_add_f32_e32 v224, v224, v188
	v_exp_f32_e32 v196, v196
	v_exp_f32_e32 v197, v197
	v_exp_f32_e32 v198, v198
	v_exp_f32_e32 v199, v199
	v_mfma_f32_16x16x32_bf16 v[128:131], v[16:19], v[246:249], v[128:131]
	v_exp_f32_e32 v200, v200
	v_exp_f32_e32 v201, v201
	v_exp_f32_e32 v202, v202
	v_exp_f32_e32 v203, v203
	v_mfma_f32_16x16x32_bf16 v[124:127], v[12:15], v[246:249], v[124:127]
	v_cvt_pk_bf16_f32 v92, v196, v197
	v_cvt_pk_bf16_f32 v93, v198, v199
	v_cvt_pk_bf16_f32 v94, v200, v201
	v_cvt_pk_bf16_f32 v95, v202, v203
	v_mfma_f32_16x16x32_bf16 v[120:123], v[8:11], v[246:249], v[120:123]
	v_add_f32_e32 v196, v196, v197
	v_add_f32_e32 v198, v198, v199
	v_add_f32_e32 v200, v200, v201
	v_add_f32_e32 v202, v202, v203
	v_mfma_f32_16x16x32_bf16 v[116:119], v[4:7], v[246:249], v[116:119]
	v_add_f32_e32 v196, v196, v198
	v_add_f32_e32 v200, v200, v202
	v_add_f32_e32 v196, v196, v200
	v_add_f32_e32 v225, v225, v196
	v_mfma_f32_16x16x32_bf16 v[112:115], v[16:19], v[92:95], v[112:115]
	v_mfma_f32_16x16x32_bf16 v[108:111], v[12:15], v[92:95], v[108:111]
	v_mfma_f32_16x16x32_bf16 v[104:107], v[8:11], v[92:95], v[104:107]
	v_mfma_f32_16x16x32_bf16 v[100:103], v[4:7], v[92:95], v[100:103]
	s_sub_u32 s91, s91, 1
	s_cmp_lg_u32 s91, 0
	s_cbranch_scc1 .Latt_CA
.Latt_cdone:
	s_nop 7
	s_cmp_eq_u32 s76, 8
	s_cbranch_scc0 .Latt_end
	s_waitcnt lgkmcnt(0)
	s_waitcnt vmcnt(0)
	s_cmp_gt_i32 s63, -2
	s_cbranch_scc0 .Latt_eb23
	s_barrier
.Latt_eb23:
	s_sub_i32 s63, s63, 2
	s_waitcnt lgkmcnt(0)
	s_waitcnt vmcnt(0)
	s_cmp_gt_i32 s63, -2
	s_cbranch_scc0 .Latt_eb24
	s_barrier
.Latt_eb24:
	s_sub_i32 s63, s63, 2
